# final RMSNorm grid-256 fast path: 8 rows per wave loaded up front, DPP/permlane-swap wave sum instead of ds_bpermute chain; far run-once branches via mid-file hop
# baseline (speedup 1.0000x reference)
; __device__ __forceinline__ int opaque_tid() { int t = threadIdx.x; asm volatile("" : "+v"(t)); return t; }
; __device__ __forceinline__ f32x4 ld4bf(const bf16* p) { const v2u w = *(const v2u*)p; return (f32x4){bf_lo(w.x), bf_hi(w.x), bf_lo(w.y), bf_hi(w.y)}; }
; __device__ __forceinline__ void final_norm(const bf16* X, const float* g, float* out, int vcu, int G, int wave, int lane) {
;     const int gw = vcu * NWAVES + wave, NGW = G * NWAVES;
;     f32x4 gv[4];
; #pragma unroll
;     for (int j = 0; j < 4; ++j) gv[j] = ((const f32x4*)g)[lane + 64 * j];
;     for (int m0 = gw; m0 < M; m0 += 2 * NGW) {
;         f32x4 v[2][4]; float rs[2];
; #pragma unroll
;         for (int u = 0; u < 2; ++u) { const int m = m0 + u * NGW; const bf16* xr = X + (size_t)(m < M ? m : m0) * DM + 4 * lane;
; #pragma unroll
;             for (int j = 0; j < 4; ++j) v[u][j] = ld4bf(xr + 256 * j); }
; #pragma unroll
;         for (int u = 0; u < 2; ++u) { float s = 0.f;
; #pragma unroll
;             for (int j = 0; j < 4; ++j) s += (v[u][j][0] * v[u][j][0] + v[u][j][1] * v[u][j][1]) + (v[u][j][2] * v[u][j][2] + v[u][j][3] * v[u][j][3]);
;             s = wave_sum(s); rs[u] = 1.0f / sqrtf(s * (1.0f / 1024.0f) + 1e-6f); }
; __global__ void __launch_bounds__(NWAVES * 64, 2) trunk_fwd(Args args) {
;     ...
;     for (int ph = args.ph_lo; ph < args.ph_hi; ++ph) {
;         if (ph == 8) continue;
;         const int tid = opaque_tid(), lane = tid & 63, wave = __builtin_amdgcn_readfirstlane(tid >> 6);
;         int Gp = Gk; asm volatile("" : "+s"(Gp));
;         const int G = Gp;
;         if (ph == 0) {
;             if (PM & 1) prologue(args, lds, vcu, G, wave, lane, tid);
;         } else if (ph == N_PHASES - 1) {
;             final_norm(XB, args.in[13], X, vcu, G, wave, lane);
.LBB0_11:
	s_cmp_eq_u32 s66, 8
	s_cbranch_scc1 .LBB0_10
	v_mov_b32_e32 v221, v0
	v_readlane_b32 s65, v253, 2
	v_readfirstlane_b32 s0, v221
	s_ashr_i32 s70, s0, 6
	s_mov_b64 s[6:7], -1
	s_mov_b64 s[0:1], 0
	s_cmp_lt_i32 s66, 21
	s_mov_b64 s[4:5], 0
	s_cbranch_scc1 .LBB0_21
	s_cmp_eq_u32 s66, 21
	s_mov_b64 s[4:5], -1
	s_cbranch_scc0 .LBB0_20
	s_add_i32 s10, s70, s85
	s_cmpk_gt_i32 s10, 0x3fff
	s_cbranch_scc1 .LBB0_19
	v_and_b32_e32 v18, 63, v221
	v_lshlrev_b32_e32 v98, 4, v18
	s_waitcnt lgkmcnt(0)
	global_load_dwordx4 v[2:5], v98, s[58:59]
	global_load_dwordx4 v[6:9], v98, s[58:59] offset:1024
	global_load_dwordx4 v[10:13], v98, s[58:59] offset:2048
	global_load_dwordx4 v[14:17], v98, s[58:59] offset:3072
	v_xor_b32_e32 v20, 1, v212
	v_cmp_lt_i32_e32 vcc, v20, v213
	v_lshlrev_b32_e32 v18, 3, v18
	v_mov_b32_e32 v19, v99
	v_cndmask_b32_e32 v20, v212, v20, vcc
	v_lshlrev_b32_e32 v56, 2, v20
	v_xor_b32_e32 v20, 2, v212
	v_cmp_lt_i32_e32 vcc, v20, v213
	s_lshl_b32 s2, s65, 3
	v_lshl_add_u64 v[18:19], s[96:97], 0, v[18:19]
	v_cndmask_b32_e32 v20, v212, v20, vcc
	v_lshlrev_b32_e32 v57, 2, v20
	v_xor_b32_e32 v20, 4, v212
	v_cmp_lt_i32_e32 vcc, v20, v213
	s_nop 1
	v_cndmask_b32_e32 v20, v212, v20, vcc
	v_lshlrev_b32_e32 v58, 2, v20
	v_xor_b32_e32 v20, 8, v212
	v_cmp_lt_i32_e32 vcc, v20, v213
	s_nop 1
	v_cndmask_b32_e32 v20, v212, v20, vcc
	v_cmp_lt_i32_e32 vcc, v252, v213
	v_lshlrev_b32_e32 v59, 2, v20
	s_nop 0
	v_cndmask_b32_e32 v20, v212, v252, vcc
	v_cmp_lt_i32_e32 vcc, v211, v213
	v_lshlrev_b32_e32 v60, 2, v20
	s_nop 0
	v_cndmask_b32_e32 v20, v212, v211, vcc
	v_lshlrev_b32_e32 v61, 2, v20
	v_lshl_add_u64 v[20:21], s[60:61], 0, v[98:99]
	s_cmp_lg_u32 s65, 0x100
	s_cbranch_scc1 .LBB0_17
	s_ashr_i32 s11, s10, 31
	s_lshl_b64 s[4:5], s[10:11], 11
	v_lshl_add_u64 v[22:23], v[18:19], 0, s[4:5]
	s_lshl_b64 s[4:5], s[10:11], 12
	v_lshl_add_u64 v[24:25], v[20:21], 0, s[4:5]
	s_mov_b64 s[6:7], 0x400000
	global_load_dwordx2 v[100:101], v[22:23], off
	global_load_dwordx2 v[102:103], v[22:23], off offset:512
	global_load_dwordx2 v[104:105], v[22:23], off offset:1024
	global_load_dwordx2 v[106:107], v[22:23], off offset:1536
	v_lshl_add_u64 v[22:23], v[22:23], 0, s[6:7]
	global_load_dwordx2 v[108:109], v[22:23], off
	global_load_dwordx2 v[110:111], v[22:23], off offset:512
	global_load_dwordx2 v[112:113], v[22:23], off offset:1024
	global_load_dwordx2 v[114:115], v[22:23], off offset:1536
	v_lshl_add_u64 v[22:23], v[22:23], 0, s[6:7]
	global_load_dwordx2 v[116:117], v[22:23], off
	global_load_dwordx2 v[118:119], v[22:23], off offset:512
	global_load_dwordx2 v[120:121], v[22:23], off offset:1024
	global_load_dwordx2 v[122:123], v[22:23], off offset:1536
	v_lshl_add_u64 v[22:23], v[22:23], 0, s[6:7]
	global_load_dwordx2 v[124:125], v[22:23], off
	global_load_dwordx2 v[126:127], v[22:23], off offset:512
	global_load_dwordx2 v[128:129], v[22:23], off offset:1024
	global_load_dwordx2 v[130:131], v[22:23], off offset:1536
	v_lshl_add_u64 v[22:23], v[22:23], 0, s[6:7]
	global_load_dwordx2 v[132:133], v[22:23], off
	global_load_dwordx2 v[134:135], v[22:23], off offset:512
	global_load_dwordx2 v[136:137], v[22:23], off offset:1024
	global_load_dwordx2 v[138:139], v[22:23], off offset:1536
	v_lshl_add_u64 v[22:23], v[22:23], 0, s[6:7]
	global_load_dwordx2 v[140:141], v[22:23], off
	global_load_dwordx2 v[142:143], v[22:23], off offset:512
	global_load_dwordx2 v[144:145], v[22:23], off offset:1024
	global_load_dwordx2 v[146:147], v[22:23], off offset:1536
	v_lshl_add_u64 v[22:23], v[22:23], 0, s[6:7]
	global_load_dwordx2 v[148:149], v[22:23], off
	global_load_dwordx2 v[150:151], v[22:23], off offset:512
	global_load_dwordx2 v[152:153], v[22:23], off offset:1024
	global_load_dwordx2 v[154:155], v[22:23], off offset:1536
	v_lshl_add_u64 v[22:23], v[22:23], 0, s[6:7]
	global_load_dwordx2 v[156:157], v[22:23], off
	global_load_dwordx2 v[158:159], v[22:23], off offset:512
	global_load_dwordx2 v[160:161], v[22:23], off offset:1024
	global_load_dwordx2 v[162:163], v[22:23], off offset:1536
	s_mov_b64 s[6:7], 0x800000
	s_waitcnt vmcnt(28)
	v_lshlrev_b32_e32 v40, 16, v100
	v_and_b32_e32 v41, 0xffff0000, v100
	v_lshlrev_b32_e32 v42, 16, v101
	v_and_b32_e32 v43, 0xffff0000, v101
	v_lshlrev_b32_e32 v44, 16, v102
	v_and_b32_e32 v45, 0xffff0000, v102
	v_lshlrev_b32_e32 v46, 16, v103
	v_and_b32_e32 v47, 0xffff0000, v103
	v_lshlrev_b32_e32 v48, 16, v104
	v_and_b32_e32 v49, 0xffff0000, v104
	v_lshlrev_b32_e32 v50, 16, v105
	v_and_b32_e32 v51, 0xffff0000, v105
	v_lshlrev_b32_e32 v52, 16, v106
	v_and_b32_e32 v53, 0xffff0000, v106
	v_lshlrev_b32_e32 v54, 16, v107
	v_and_b32_e32 v55, 0xffff0000, v107
	v_mul_f32_e32 v60, v41, v41
	v_fmac_f32_e32 v60, v40, v40
	v_mul_f32_e32 v61, v43, v43
	v_fmac_f32_e32 v61, v42, v42
	v_add_f32_e32 v62, v60, v61
	v_mul_f32_e32 v60, v45, v45
	v_fmac_f32_e32 v60, v44, v44
	v_mul_f32_e32 v61, v47, v47
	v_fmac_f32_e32 v61, v46, v46
	v_add_f32_e32 v60, v60, v61
	v_add_f32_e32 v62, v62, v60
	v_mul_f32_e32 v60, v49, v49
	v_fmac_f32_e32 v60, v48, v48
	v_mul_f32_e32 v61, v51, v51
	v_fmac_f32_e32 v61, v50, v50
	v_add_f32_e32 v60, v60, v61
	v_add_f32_e32 v62, v62, v60
	v_mul_f32_e32 v60, v53, v53
	v_fmac_f32_e32 v60, v52, v52
	v_mul_f32_e32 v61, v55, v55
	v_fmac_f32_e32 v61, v54, v54
	v_add_f32_e32 v60, v60, v61
	v_add_f32_e32 v62, v62, v60
	s_nop 1
	v_add_f32_dpp v62, v62, v62 quad_perm:[1,0,3,2] row_mask:0xf bank_mask:0xf
	s_nop 1
	v_add_f32_dpp v62, v62, v62 quad_perm:[2,3,0,1] row_mask:0xf bank_mask:0xf
	s_nop 1
	v_add_f32_dpp v62, v62, v62 row_half_mirror row_mask:0xf bank_mask:0xf
	s_nop 1
	v_add_f32_dpp v62, v62, v62 row_mirror row_mask:0xf bank_mask:0xf
; __device__ __forceinline__ float wave_sum(float v) {
; #pragma unroll
;     for (int o = 1; o < 64; o <<= 1) v += __shfl_xor(v, o);
;     return v;
; }
; __device__ __forceinline__ void final_norm(const bf16* X, const float* g, float* out, int vcu, int G, int wave, int lane) {
;     ...
;         for (int u = 0; u < 2; ++u) { float s = 0.f;
; #pragma unroll
;             for (int j = 0; j < 4; ++j) s += (v[u][j][0] * v[u][j][0] + v[u][j][1] * v[u][j][1]) + (v[u][j][2] * v[u][j][2] + v[u][j][3] * v[u][j][3]);
;             s = wave_sum(s); rs[u] = 1.0f / sqrtf(s * (1.0f / 1024.0f) + 1e-6f); }
; #pragma unroll
;         for (int u = 0; u < 2; ++u) { const int m = m0 + u * NGW; if (m < M) { f32x4* o = (f32x4*)(out + (size_t)m * DM) + lane;
; #pragma unroll
;             for (int j = 0; j < 4; ++j) o[64 * j] = v[u][j] * rs[u] * gv[j]; } }
	v_mov_b32_e32 v63, v62
	v_mov_b32_e32 v64, v62
	s_nop 1
	v_permlane16_swap_b32_e32 v63, v64
	v_add_f32_e32 v63, v63, v64
	v_mov_b32_e32 v64, v63
	s_nop 1
	v_permlane32_swap_b32_e32 v63, v64
	v_add_f32_e32 v62, v63, v64
	v_fmamk_f32 v62, v62, 0x3a800000, v1
	v_mul_f32_e32 v63, 0x4f800000, v62
	v_cmp_gt_f32_e32 vcc, s3, v62
	s_nop 1
	v_cndmask_b32_e32 v62, v62, v63, vcc
	v_sqrt_f32_e32 v63, v62
	s_nop 0
	v_add_u32_e32 v32, -1, v63
	v_add_u32_e32 v64, 1, v63
	v_fma_f32 v65, -v32, v63, v62
	v_fma_f32 v66, -v64, v63, v62
	v_cmp_ge_f32_e64 s[36:37], 0, v65
	s_nop 1
	v_cndmask_b32_e64 v32, v63, v32, s[36:37]
	v_cmp_lt_f32_e64 s[36:37], 0, v66
	s_nop 1
	v_cndmask_b32_e64 v32, v32, v64, s[36:37]
	v_mul_f32_e32 v63, 0x37800000, v32
	v_cndmask_b32_e32 v32, v32, v63, vcc
	v_cmp_class_f32_e32 vcc, v62, v210
	s_nop 1
	v_cndmask_b32_e32 v32, v32, v62, vcc
	v_div_scale_f32 v63, s[8:9], v32, v32, 1.0
	v_rcp_f32_e32 v64, v63
	v_div_scale_f32 v65, vcc, 1.0, v32, 1.0
	v_fma_f32 v66, -v63, v64, 1.0
	v_fmac_f32_e32 v64, v66, v64
	v_mul_f32_e32 v66, v65, v64
	v_fma_f32 v67, -v63, v66, v65
	v_fmac_f32_e32 v66, v67, v64
	v_fma_f32 v63, -v63, v66, v65
	s_nop 1
	v_div_fmas_f32 v63, v63, v64, v66
	v_div_fixup_f32 v68, v63, v32, 1.0
	v_mul_f32_e32 v40, v68, v40
	v_mul_f32_e32 v41, v68, v41
	v_mul_f32_e32 v42, v68, v42
	v_mul_f32_e32 v43, v68, v43
	v_mul_f32_e32 v40, v2, v40
	v_mul_f32_e32 v41, v3, v41
	v_mul_f32_e32 v42, v4, v42
	v_mul_f32_e32 v43, v5, v43
	global_store_dwordx4 v[24:25], v[40:43], off
	v_mul_f32_e32 v44, v68, v44
	v_mul_f32_e32 v45, v68, v45
	v_mul_f32_e32 v46, v68, v46
	v_mul_f32_e32 v47, v68, v47
	v_mul_f32_e32 v44, v6, v44
	v_mul_f32_e32 v45, v7, v45
	v_mul_f32_e32 v46, v8, v46
	v_mul_f32_e32 v47, v9, v47
	global_store_dwordx4 v[24:25], v[44:47], off offset:1024
	v_mul_f32_e32 v48, v68, v48
	v_mul_f32_e32 v49, v68, v49
	v_mul_f32_e32 v50, v68, v50
	v_mul_f32_e32 v51, v68, v51
	v_mul_f32_e32 v48, v10, v48
	v_mul_f32_e32 v49, v11, v49
	v_mul_f32_e32 v50, v12, v50
	v_mul_f32_e32 v51, v13, v51
	global_store_dwordx4 v[24:25], v[48:51], off offset:2048
	v_mul_f32_e32 v52, v68, v52
	v_mul_f32_e32 v53, v68, v53
	v_mul_f32_e32 v54, v68, v54
	v_mul_f32_e32 v55, v68, v55
	v_mul_f32_e32 v52, v14, v52
	v_mul_f32_e32 v53, v15, v53
	v_mul_f32_e32 v54, v16, v54
	v_mul_f32_e32 v55, v17, v55
	global_store_dwordx4 v[24:25], v[52:55], off offset:3072
	v_lshl_add_u64 v[24:25], v[24:25], 0, s[6:7]
	s_waitcnt vmcnt(28)
	v_lshlrev_b32_e32 v40, 16, v108
	v_and_b32_e32 v41, 0xffff0000, v108
	v_lshlrev_b32_e32 v42, 16, v109
	v_and_b32_e32 v43, 0xffff0000, v109
	v_lshlrev_b32_e32 v44, 16, v110
	v_and_b32_e32 v45, 0xffff0000, v110
	v_lshlrev_b32_e32 v46, 16, v111
	v_and_b32_e32 v47, 0xffff0000, v111
	v_lshlrev_b32_e32 v48, 16, v112
	v_and_b32_e32 v49, 0xffff0000, v112
	v_lshlrev_b32_e32 v50, 16, v113
	v_and_b32_e32 v51, 0xffff0000, v113
	v_lshlrev_b32_e32 v52, 16, v114
	v_and_b32_e32 v53, 0xffff0000, v114
	v_lshlrev_b32_e32 v54, 16, v115
	v_and_b32_e32 v55, 0xffff0000, v115
	v_mul_f32_e32 v60, v41, v41
	v_fmac_f32_e32 v60, v40, v40
	v_mul_f32_e32 v61, v43, v43
	v_fmac_f32_e32 v61, v42, v42
	v_add_f32_e32 v62, v60, v61
	v_mul_f32_e32 v60, v45, v45
	v_fmac_f32_e32 v60, v44, v44
	v_mul_f32_e32 v61, v47, v47
	v_fmac_f32_e32 v61, v46, v46
	v_add_f32_e32 v60, v60, v61
	v_add_f32_e32 v62, v62, v60
	v_mul_f32_e32 v60, v49, v49
	v_fmac_f32_e32 v60, v48, v48
	v_mul_f32_e32 v61, v51, v51
	v_fmac_f32_e32 v61, v50, v50
	v_add_f32_e32 v60, v60, v61
	v_add_f32_e32 v62, v62, v60
	v_mul_f32_e32 v60, v53, v53
	v_fmac_f32_e32 v60, v52, v52
	v_mul_f32_e32 v61, v55, v55
	v_fmac_f32_e32 v61, v54, v54
	v_add_f32_e32 v60, v60, v61
	v_add_f32_e32 v62, v62, v60
	s_nop 1
	v_add_f32_dpp v62, v62, v62 quad_perm:[1,0,3,2] row_mask:0xf bank_mask:0xf
	s_nop 1
	v_add_f32_dpp v62, v62, v62 quad_perm:[2,3,0,1] row_mask:0xf bank_mask:0xf
	s_nop 1
	v_add_f32_dpp v62, v62, v62 row_half_mirror row_mask:0xf bank_mask:0xf
	s_nop 1
	v_add_f32_dpp v62, v62, v62 row_mirror row_mask:0xf bank_mask:0xf
	v_mov_b32_e32 v63, v62
	v_mov_b32_e32 v64, v62
	s_nop 1
	v_permlane16_swap_b32_e32 v63, v64
	v_add_f32_e32 v63, v63, v64
	v_mov_b32_e32 v64, v63
	s_nop 1
	v_permlane32_swap_b32_e32 v63, v64
	v_add_f32_e32 v62, v63, v64
	v_fmamk_f32 v62, v62, 0x3a800000, v1
	v_mul_f32_e32 v63, 0x4f800000, v62
	v_cmp_gt_f32_e32 vcc, s3, v62
	s_nop 1
	v_cndmask_b32_e32 v62, v62, v63, vcc
	v_sqrt_f32_e32 v63, v62
	s_nop 0
	v_add_u32_e32 v32, -1, v63
	v_add_u32_e32 v64, 1, v63
	v_fma_f32 v65, -v32, v63, v62
	v_fma_f32 v66, -v64, v63, v62
	v_cmp_ge_f32_e64 s[36:37], 0, v65
	s_nop 1
	v_cndmask_b32_e64 v32, v63, v32, s[36:37]
	v_cmp_lt_f32_e64 s[36:37], 0, v66
	s_nop 1
	v_cndmask_b32_e64 v32, v32, v64, s[36:37]
	v_mul_f32_e32 v63, 0x37800000, v32
	v_cndmask_b32_e32 v32, v32, v63, vcc
	v_cmp_class_f32_e32 vcc, v62, v210
	s_nop 1
	v_cndmask_b32_e32 v32, v32, v62, vcc
	v_div_scale_f32 v63, s[8:9], v32, v32, 1.0
	v_rcp_f32_e32 v64, v63
	v_div_scale_f32 v65, vcc, 1.0, v32, 1.0
	v_fma_f32 v66, -v63, v64, 1.0
	v_fmac_f32_e32 v64, v66, v64
	v_mul_f32_e32 v66, v65, v64
	v_fma_f32 v67, -v63, v66, v65
	v_fmac_f32_e32 v66, v67, v64
	v_fma_f32 v63, -v63, v66, v65
	s_nop 1
	v_div_fmas_f32 v63, v63, v64, v66
	v_div_fixup_f32 v68, v63, v32, 1.0
	v_mul_f32_e32 v40, v68, v40
	v_mul_f32_e32 v41, v68, v41
	v_mul_f32_e32 v42, v68, v42
	v_mul_f32_e32 v43, v68, v43
	v_mul_f32_e32 v40, v2, v40
	v_mul_f32_e32 v41, v3, v41
	v_mul_f32_e32 v42, v4, v42
	v_mul_f32_e32 v43, v5, v43
	global_store_dwordx4 v[24:25], v[40:43], off
	v_mul_f32_e32 v44, v68, v44
	v_mul_f32_e32 v45, v68, v45
	v_mul_f32_e32 v46, v68, v46
	v_mul_f32_e32 v47, v68, v47
	v_mul_f32_e32 v44, v6, v44
	v_mul_f32_e32 v45, v7, v45
	v_mul_f32_e32 v46, v8, v46
	v_mul_f32_e32 v47, v9, v47
	global_store_dwordx4 v[24:25], v[44:47], off offset:1024
	v_mul_f32_e32 v48, v68, v48
	v_mul_f32_e32 v49, v68, v49
	v_mul_f32_e32 v50, v68, v50
	v_mul_f32_e32 v51, v68, v51
	v_mul_f32_e32 v48, v10, v48
	v_mul_f32_e32 v49, v11, v49
	v_mul_f32_e32 v50, v12, v50
	v_mul_f32_e32 v51, v13, v51
	global_store_dwordx4 v[24:25], v[48:51], off offset:2048
	v_mul_f32_e32 v52, v68, v52
	v_mul_f32_e32 v53, v68, v53
	v_mul_f32_e32 v54, v68, v54
	v_mul_f32_e32 v55, v68, v55
	v_mul_f32_e32 v52, v14, v52
	v_mul_f32_e32 v53, v15, v53
	v_mul_f32_e32 v54, v16, v54
	v_mul_f32_e32 v55, v17, v55
	global_store_dwordx4 v[24:25], v[52:55], off offset:3072
	v_lshl_add_u64 v[24:25], v[24:25], 0, s[6:7]
	s_waitcnt vmcnt(28)
; __device__ __forceinline__ void final_norm(const bf16* X, const float* g, float* out, int vcu, int G, int wave, int lane) {
;     ...
;         for (int u = 0; u < 2; ++u) { float s = 0.f;
; #pragma unroll
;             for (int j = 0; j < 4; ++j) s += (v[u][j][0] * v[u][j][0] + v[u][j][1] * v[u][j][1]) + (v[u][j][2] * v[u][j][2] + v[u][j][3] * v[u][j][3]);
;             s = wave_sum(s); rs[u] = 1.0f / sqrtf(s * (1.0f / 1024.0f) + 1e-6f); }
; #pragma unroll
;         for (int u = 0; u < 2; ++u) { const int m = m0 + u * NGW; if (m < M) { f32x4* o = (f32x4*)(out + (size_t)m * DM) + lane;
; #pragma unroll
;             for (int j = 0; j < 4; ++j) o[64 * j] = v[u][j] * rs[u] * gv[j]; } }
	v_lshlrev_b32_e32 v40, 16, v116
	v_and_b32_e32 v41, 0xffff0000, v116
	v_lshlrev_b32_e32 v42, 16, v117
	v_and_b32_e32 v43, 0xffff0000, v117
	v_lshlrev_b32_e32 v44, 16, v118
	v_and_b32_e32 v45, 0xffff0000, v118
	v_lshlrev_b32_e32 v46, 16, v119
	v_and_b32_e32 v47, 0xffff0000, v119
	v_lshlrev_b32_e32 v48, 16, v120
	v_and_b32_e32 v49, 0xffff0000, v120
	v_lshlrev_b32_e32 v50, 16, v121
	v_and_b32_e32 v51, 0xffff0000, v121
	v_lshlrev_b32_e32 v52, 16, v122
	v_and_b32_e32 v53, 0xffff0000, v122
	v_lshlrev_b32_e32 v54, 16, v123
	v_and_b32_e32 v55, 0xffff0000, v123
	v_mul_f32_e32 v60, v41, v41
	v_fmac_f32_e32 v60, v40, v40
	v_mul_f32_e32 v61, v43, v43
	v_fmac_f32_e32 v61, v42, v42
	v_add_f32_e32 v62, v60, v61
	v_mul_f32_e32 v60, v45, v45
	v_fmac_f32_e32 v60, v44, v44
	v_mul_f32_e32 v61, v47, v47
	v_fmac_f32_e32 v61, v46, v46
	v_add_f32_e32 v60, v60, v61
	v_add_f32_e32 v62, v62, v60
	v_mul_f32_e32 v60, v49, v49
	v_fmac_f32_e32 v60, v48, v48
	v_mul_f32_e32 v61, v51, v51
	v_fmac_f32_e32 v61, v50, v50
	v_add_f32_e32 v60, v60, v61
	v_add_f32_e32 v62, v62, v60
	v_mul_f32_e32 v60, v53, v53
	v_fmac_f32_e32 v60, v52, v52
	v_mul_f32_e32 v61, v55, v55
	v_fmac_f32_e32 v61, v54, v54
	v_add_f32_e32 v60, v60, v61
	v_add_f32_e32 v62, v62, v60
	s_nop 1
	v_add_f32_dpp v62, v62, v62 quad_perm:[1,0,3,2] row_mask:0xf bank_mask:0xf
	s_nop 1
	v_add_f32_dpp v62, v62, v62 quad_perm:[2,3,0,1] row_mask:0xf bank_mask:0xf
	s_nop 1
	v_add_f32_dpp v62, v62, v62 row_half_mirror row_mask:0xf bank_mask:0xf
	s_nop 1
	v_add_f32_dpp v62, v62, v62 row_mirror row_mask:0xf bank_mask:0xf
	v_mov_b32_e32 v63, v62
	v_mov_b32_e32 v64, v62
	s_nop 1
	v_permlane16_swap_b32_e32 v63, v64
	v_add_f32_e32 v63, v63, v64
	v_mov_b32_e32 v64, v63
	s_nop 1
	v_permlane32_swap_b32_e32 v63, v64
	v_add_f32_e32 v62, v63, v64
	v_fmamk_f32 v62, v62, 0x3a800000, v1
	v_mul_f32_e32 v63, 0x4f800000, v62
	v_cmp_gt_f32_e32 vcc, s3, v62
	s_nop 1
	v_cndmask_b32_e32 v62, v62, v63, vcc
	v_sqrt_f32_e32 v63, v62
	s_nop 0
	v_add_u32_e32 v32, -1, v63
	v_add_u32_e32 v64, 1, v63
	v_fma_f32 v65, -v32, v63, v62
	v_fma_f32 v66, -v64, v63, v62
	v_cmp_ge_f32_e64 s[36:37], 0, v65
	s_nop 1
	v_cndmask_b32_e64 v32, v63, v32, s[36:37]
	v_cmp_lt_f32_e64 s[36:37], 0, v66
	s_nop 1
	v_cndmask_b32_e64 v32, v32, v64, s[36:37]
	v_mul_f32_e32 v63, 0x37800000, v32
	v_cndmask_b32_e32 v32, v32, v63, vcc
	v_cmp_class_f32_e32 vcc, v62, v210
	s_nop 1
	v_cndmask_b32_e32 v32, v32, v62, vcc
	v_div_scale_f32 v63, s[8:9], v32, v32, 1.0
	v_rcp_f32_e32 v64, v63
	v_div_scale_f32 v65, vcc, 1.0, v32, 1.0
	v_fma_f32 v66, -v63, v64, 1.0
	v_fmac_f32_e32 v64, v66, v64
	v_mul_f32_e32 v66, v65, v64
	v_fma_f32 v67, -v63, v66, v65
	v_fmac_f32_e32 v66, v67, v64
	v_fma_f32 v63, -v63, v66, v65
	s_nop 1
	v_div_fmas_f32 v63, v63, v64, v66
	v_div_fixup_f32 v68, v63, v32, 1.0
	v_mul_f32_e32 v40, v68, v40
	v_mul_f32_e32 v41, v68, v41
	v_mul_f32_e32 v42, v68, v42
	v_mul_f32_e32 v43, v68, v43
	v_mul_f32_e32 v40, v2, v40
	v_mul_f32_e32 v41, v3, v41
	v_mul_f32_e32 v42, v4, v42
	v_mul_f32_e32 v43, v5, v43
	global_store_dwordx4 v[24:25], v[40:43], off
	v_mul_f32_e32 v44, v68, v44
	v_mul_f32_e32 v45, v68, v45
	v_mul_f32_e32 v46, v68, v46
	v_mul_f32_e32 v47, v68, v47
	v_mul_f32_e32 v44, v6, v44
	v_mul_f32_e32 v45, v7, v45
	v_mul_f32_e32 v46, v8, v46
	v_mul_f32_e32 v47, v9, v47
	global_store_dwordx4 v[24:25], v[44:47], off offset:1024
	v_mul_f32_e32 v48, v68, v48
	v_mul_f32_e32 v49, v68, v49
	v_mul_f32_e32 v50, v68, v50
	v_mul_f32_e32 v51, v68, v51
	v_mul_f32_e32 v48, v10, v48
	v_mul_f32_e32 v49, v11, v49
	v_mul_f32_e32 v50, v12, v50
	v_mul_f32_e32 v51, v13, v51
	global_store_dwordx4 v[24:25], v[48:51], off offset:2048
	v_mul_f32_e32 v52, v68, v52
	v_mul_f32_e32 v53, v68, v53
	v_mul_f32_e32 v54, v68, v54
	v_mul_f32_e32 v55, v68, v55
	v_mul_f32_e32 v52, v14, v52
	v_mul_f32_e32 v53, v15, v53
	v_mul_f32_e32 v54, v16, v54
	v_mul_f32_e32 v55, v17, v55
	global_store_dwordx4 v[24:25], v[52:55], off offset:3072
	v_lshl_add_u64 v[24:25], v[24:25], 0, s[6:7]
	s_waitcnt vmcnt(28)
	v_lshlrev_b32_e32 v40, 16, v124
	v_and_b32_e32 v41, 0xffff0000, v124
	v_lshlrev_b32_e32 v42, 16, v125
	v_and_b32_e32 v43, 0xffff0000, v125
	v_lshlrev_b32_e32 v44, 16, v126
	v_and_b32_e32 v45, 0xffff0000, v126
	v_lshlrev_b32_e32 v46, 16, v127
	v_and_b32_e32 v47, 0xffff0000, v127
	v_lshlrev_b32_e32 v48, 16, v128
	v_and_b32_e32 v49, 0xffff0000, v128
	v_lshlrev_b32_e32 v50, 16, v129
	v_and_b32_e32 v51, 0xffff0000, v129
	v_lshlrev_b32_e32 v52, 16, v130
	v_and_b32_e32 v53, 0xffff0000, v130
	v_lshlrev_b32_e32 v54, 16, v131
	v_and_b32_e32 v55, 0xffff0000, v131
	v_mul_f32_e32 v60, v41, v41
	v_fmac_f32_e32 v60, v40, v40
	v_mul_f32_e32 v61, v43, v43
	v_fmac_f32_e32 v61, v42, v42
	v_add_f32_e32 v62, v60, v61
	v_mul_f32_e32 v60, v45, v45
	v_fmac_f32_e32 v60, v44, v44
	v_mul_f32_e32 v61, v47, v47
	v_fmac_f32_e32 v61, v46, v46
	v_add_f32_e32 v60, v60, v61
	v_add_f32_e32 v62, v62, v60
	v_mul_f32_e32 v60, v49, v49
	v_fmac_f32_e32 v60, v48, v48
	v_mul_f32_e32 v61, v51, v51
	v_fmac_f32_e32 v61, v50, v50
	v_add_f32_e32 v60, v60, v61
	v_add_f32_e32 v62, v62, v60
	v_mul_f32_e32 v60, v53, v53
	v_fmac_f32_e32 v60, v52, v52
	v_mul_f32_e32 v61, v55, v55
	v_fmac_f32_e32 v61, v54, v54
	v_add_f32_e32 v60, v60, v61
	v_add_f32_e32 v62, v62, v60
	s_nop 1
	v_add_f32_dpp v62, v62, v62 quad_perm:[1,0,3,2] row_mask:0xf bank_mask:0xf
	s_nop 1
	v_add_f32_dpp v62, v62, v62 quad_perm:[2,3,0,1] row_mask:0xf bank_mask:0xf
	s_nop 1
	v_add_f32_dpp v62, v62, v62 row_half_mirror row_mask:0xf bank_mask:0xf
	s_nop 1
	v_add_f32_dpp v62, v62, v62 row_mirror row_mask:0xf bank_mask:0xf
	v_mov_b32_e32 v63, v62
	v_mov_b32_e32 v64, v62
	s_nop 1
	v_permlane16_swap_b32_e32 v63, v64
; __device__ __forceinline__ void final_norm(const bf16* X, const float* g, float* out, int vcu, int G, int wave, int lane) {
;     ...
;         for (int u = 0; u < 2; ++u) { float s = 0.f;
; #pragma unroll
;             for (int j = 0; j < 4; ++j) s += (v[u][j][0] * v[u][j][0] + v[u][j][1] * v[u][j][1]) + (v[u][j][2] * v[u][j][2] + v[u][j][3] * v[u][j][3]);
;             s = wave_sum(s); rs[u] = 1.0f / sqrtf(s * (1.0f / 1024.0f) + 1e-6f); }
; #pragma unroll
;         for (int u = 0; u < 2; ++u) { const int m = m0 + u * NGW; if (m < M) { f32x4* o = (f32x4*)(out + (size_t)m * DM) + lane;
; #pragma unroll
;             for (int j = 0; j < 4; ++j) o[64 * j] = v[u][j] * rs[u] * gv[j]; } }
	v_add_f32_e32 v63, v63, v64
	v_mov_b32_e32 v64, v63
	s_nop 1
	v_permlane32_swap_b32_e32 v63, v64
	v_add_f32_e32 v62, v63, v64
	v_fmamk_f32 v62, v62, 0x3a800000, v1
	v_mul_f32_e32 v63, 0x4f800000, v62
	v_cmp_gt_f32_e32 vcc, s3, v62
	s_nop 1
	v_cndmask_b32_e32 v62, v62, v63, vcc
	v_sqrt_f32_e32 v63, v62
	s_nop 0
	v_add_u32_e32 v32, -1, v63
	v_add_u32_e32 v64, 1, v63
	v_fma_f32 v65, -v32, v63, v62
	v_fma_f32 v66, -v64, v63, v62
	v_cmp_ge_f32_e64 s[36:37], 0, v65
	s_nop 1
	v_cndmask_b32_e64 v32, v63, v32, s[36:37]
	v_cmp_lt_f32_e64 s[36:37], 0, v66
	s_nop 1
	v_cndmask_b32_e64 v32, v32, v64, s[36:37]
	v_mul_f32_e32 v63, 0x37800000, v32
	v_cndmask_b32_e32 v32, v32, v63, vcc
	v_cmp_class_f32_e32 vcc, v62, v210
	s_nop 1
	v_cndmask_b32_e32 v32, v32, v62, vcc
	v_div_scale_f32 v63, s[8:9], v32, v32, 1.0
	v_rcp_f32_e32 v64, v63
	v_div_scale_f32 v65, vcc, 1.0, v32, 1.0
	v_fma_f32 v66, -v63, v64, 1.0
	v_fmac_f32_e32 v64, v66, v64
	v_mul_f32_e32 v66, v65, v64
	v_fma_f32 v67, -v63, v66, v65
	v_fmac_f32_e32 v66, v67, v64
	v_fma_f32 v63, -v63, v66, v65
	s_nop 1
	v_div_fmas_f32 v63, v63, v64, v66
	v_div_fixup_f32 v68, v63, v32, 1.0
	v_mul_f32_e32 v40, v68, v40
	v_mul_f32_e32 v41, v68, v41
	v_mul_f32_e32 v42, v68, v42
	v_mul_f32_e32 v43, v68, v43
	v_mul_f32_e32 v40, v2, v40
	v_mul_f32_e32 v41, v3, v41
	v_mul_f32_e32 v42, v4, v42
	v_mul_f32_e32 v43, v5, v43
	global_store_dwordx4 v[24:25], v[40:43], off
	v_mul_f32_e32 v44, v68, v44
	v_mul_f32_e32 v45, v68, v45
	v_mul_f32_e32 v46, v68, v46
	v_mul_f32_e32 v47, v68, v47
	v_mul_f32_e32 v44, v6, v44
	v_mul_f32_e32 v45, v7, v45
	v_mul_f32_e32 v46, v8, v46
	v_mul_f32_e32 v47, v9, v47
	global_store_dwordx4 v[24:25], v[44:47], off offset:1024
	v_mul_f32_e32 v48, v68, v48
	v_mul_f32_e32 v49, v68, v49
	v_mul_f32_e32 v50, v68, v50
	v_mul_f32_e32 v51, v68, v51
	v_mul_f32_e32 v48, v10, v48
	v_mul_f32_e32 v49, v11, v49
	v_mul_f32_e32 v50, v12, v50
	v_mul_f32_e32 v51, v13, v51
	global_store_dwordx4 v[24:25], v[48:51], off offset:2048
	v_mul_f32_e32 v52, v68, v52
	v_mul_f32_e32 v53, v68, v53
	v_mul_f32_e32 v54, v68, v54
	v_mul_f32_e32 v55, v68, v55
	v_mul_f32_e32 v52, v14, v52
	v_mul_f32_e32 v53, v15, v53
	v_mul_f32_e32 v54, v16, v54
	v_mul_f32_e32 v55, v17, v55
	global_store_dwordx4 v[24:25], v[52:55], off offset:3072
	v_lshl_add_u64 v[24:25], v[24:25], 0, s[6:7]
	s_waitcnt vmcnt(28)
	v_lshlrev_b32_e32 v40, 16, v132
	v_and_b32_e32 v41, 0xffff0000, v132
	v_lshlrev_b32_e32 v42, 16, v133
	v_and_b32_e32 v43, 0xffff0000, v133
	v_lshlrev_b32_e32 v44, 16, v134
	v_and_b32_e32 v45, 0xffff0000, v134
	v_lshlrev_b32_e32 v46, 16, v135
	v_and_b32_e32 v47, 0xffff0000, v135
	v_lshlrev_b32_e32 v48, 16, v136
	v_and_b32_e32 v49, 0xffff0000, v136
	v_lshlrev_b32_e32 v50, 16, v137
	v_and_b32_e32 v51, 0xffff0000, v137
	v_lshlrev_b32_e32 v52, 16, v138
	v_and_b32_e32 v53, 0xffff0000, v138
	v_lshlrev_b32_e32 v54, 16, v139
	v_and_b32_e32 v55, 0xffff0000, v139
	v_mul_f32_e32 v60, v41, v41
	v_fmac_f32_e32 v60, v40, v40
	v_mul_f32_e32 v61, v43, v43
	v_fmac_f32_e32 v61, v42, v42
	v_add_f32_e32 v62, v60, v61
	v_mul_f32_e32 v60, v45, v45
	v_fmac_f32_e32 v60, v44, v44
	v_mul_f32_e32 v61, v47, v47
	v_fmac_f32_e32 v61, v46, v46
	v_add_f32_e32 v60, v60, v61
	v_add_f32_e32 v62, v62, v60
	v_mul_f32_e32 v60, v49, v49
	v_fmac_f32_e32 v60, v48, v48
	v_mul_f32_e32 v61, v51, v51
	v_fmac_f32_e32 v61, v50, v50
	v_add_f32_e32 v60, v60, v61
	v_add_f32_e32 v62, v62, v60
	v_mul_f32_e32 v60, v53, v53
	v_fmac_f32_e32 v60, v52, v52
	v_mul_f32_e32 v61, v55, v55
	v_fmac_f32_e32 v61, v54, v54
	v_add_f32_e32 v60, v60, v61
	v_add_f32_e32 v62, v62, v60
	s_nop 1
	v_add_f32_dpp v62, v62, v62 quad_perm:[1,0,3,2] row_mask:0xf bank_mask:0xf
	s_nop 1
	v_add_f32_dpp v62, v62, v62 quad_perm:[2,3,0,1] row_mask:0xf bank_mask:0xf
	s_nop 1
	v_add_f32_dpp v62, v62, v62 row_half_mirror row_mask:0xf bank_mask:0xf
	s_nop 1
	v_add_f32_dpp v62, v62, v62 row_mirror row_mask:0xf bank_mask:0xf
	v_mov_b32_e32 v63, v62
	v_mov_b32_e32 v64, v62
	s_nop 1
	v_permlane16_swap_b32_e32 v63, v64
	v_add_f32_e32 v63, v63, v64
	v_mov_b32_e32 v64, v63
	s_nop 1
	v_permlane32_swap_b32_e32 v63, v64
	v_add_f32_e32 v62, v63, v64
	v_fmamk_f32 v62, v62, 0x3a800000, v1
	v_mul_f32_e32 v63, 0x4f800000, v62
	v_cmp_gt_f32_e32 vcc, s3, v62
	s_nop 1
	v_cndmask_b32_e32 v62, v62, v63, vcc
	v_sqrt_f32_e32 v63, v62
	s_nop 0
	v_add_u32_e32 v32, -1, v63
	v_add_u32_e32 v64, 1, v63
	v_fma_f32 v65, -v32, v63, v62
	v_fma_f32 v66, -v64, v63, v62
	v_cmp_ge_f32_e64 s[36:37], 0, v65
	s_nop 1
	v_cndmask_b32_e64 v32, v63, v32, s[36:37]
	v_cmp_lt_f32_e64 s[36:37], 0, v66
	s_nop 1
	v_cndmask_b32_e64 v32, v32, v64, s[36:37]
	v_mul_f32_e32 v63, 0x37800000, v32
	v_cndmask_b32_e32 v32, v32, v63, vcc
	v_cmp_class_f32_e32 vcc, v62, v210
	s_nop 1
	v_cndmask_b32_e32 v32, v32, v62, vcc
	v_div_scale_f32 v63, s[8:9], v32, v32, 1.0
	v_rcp_f32_e32 v64, v63
	v_div_scale_f32 v65, vcc, 1.0, v32, 1.0
	v_fma_f32 v66, -v63, v64, 1.0
	v_fmac_f32_e32 v64, v66, v64
	v_mul_f32_e32 v66, v65, v64
	v_fma_f32 v67, -v63, v66, v65
	v_fmac_f32_e32 v66, v67, v64
	v_fma_f32 v63, -v63, v66, v65
	s_nop 1
	v_div_fmas_f32 v63, v63, v64, v66
	v_div_fixup_f32 v68, v63, v32, 1.0
	v_mul_f32_e32 v40, v68, v40
	v_mul_f32_e32 v41, v68, v41
	v_mul_f32_e32 v42, v68, v42
	v_mul_f32_e32 v43, v68, v43
	v_mul_f32_e32 v40, v2, v40
	v_mul_f32_e32 v41, v3, v41
	v_mul_f32_e32 v42, v4, v42
	v_mul_f32_e32 v43, v5, v43
	global_store_dwordx4 v[24:25], v[40:43], off
	v_mul_f32_e32 v44, v68, v44
	v_mul_f32_e32 v45, v68, v45
	v_mul_f32_e32 v46, v68, v46
	v_mul_f32_e32 v47, v68, v47
	v_mul_f32_e32 v44, v6, v44
	v_mul_f32_e32 v45, v7, v45
	v_mul_f32_e32 v46, v8, v46
	v_mul_f32_e32 v47, v9, v47
	global_store_dwordx4 v[24:25], v[44:47], off offset:1024
	v_mul_f32_e32 v48, v68, v48
	v_mul_f32_e32 v49, v68, v49
	v_mul_f32_e32 v50, v68, v50
	v_mul_f32_e32 v51, v68, v51
	v_mul_f32_e32 v48, v10, v48
	v_mul_f32_e32 v49, v11, v49
	v_mul_f32_e32 v50, v12, v50
	v_mul_f32_e32 v51, v13, v51
	global_store_dwordx4 v[24:25], v[48:51], off offset:2048
	v_mul_f32_e32 v52, v68, v52
	v_mul_f32_e32 v53, v68, v53
	v_mul_f32_e32 v54, v68, v54
	v_mul_f32_e32 v55, v68, v55
	v_mul_f32_e32 v52, v14, v52
	v_mul_f32_e32 v53, v15, v53
	v_mul_f32_e32 v54, v16, v54
	v_mul_f32_e32 v55, v17, v55
	global_store_dwordx4 v[24:25], v[52:55], off offset:3072
	v_lshl_add_u64 v[24:25], v[24:25], 0, s[6:7]
	s_waitcnt vmcnt(28)
; __device__ __forceinline__ f32x4 ld4bf(const bf16* p) { const v2u w = *(const v2u*)p; return (f32x4){bf_lo(w.x), bf_hi(w.x), bf_lo(w.y), bf_hi(w.y)}; }
; __device__ __forceinline__ void final_norm(const bf16* X, const float* g, float* out, int vcu, int G, int wave, int lane) {
;     ...
;     for (int m0 = gw; m0 < M; m0 += 2 * NGW) {
;         f32x4 v[2][4]; float rs[2];
; #pragma unroll
;         for (int u = 0; u < 2; ++u) { const int m = m0 + u * NGW; const bf16* xr = X + (size_t)(m < M ? m : m0) * DM + 4 * lane;
; #pragma unroll
;             for (int j = 0; j < 4; ++j) v[u][j] = ld4bf(xr + 256 * j); }
; #pragma unroll
;         for (int u = 0; u < 2; ++u) { float s = 0.f;
; #pragma unroll
;             for (int j = 0; j < 4; ++j) s += (v[u][j][0] * v[u][j][0] + v[u][j][1] * v[u][j][1]) + (v[u][j][2] * v[u][j][2] + v[u][j][3] * v[u][j][3]);
;             s = wave_sum(s); rs[u] = 1.0f / sqrtf(s * (1.0f / 1024.0f) + 1e-6f); }
; #pragma unroll
;         for (int u = 0; u < 2; ++u) { const int m = m0 + u * NGW; if (m < M) { f32x4* o = (f32x4*)(out + (size_t)m * DM) + lane;
; #pragma unroll
;             for (int j = 0; j < 4; ++j) o[64 * j] = v[u][j] * rs[u] * gv[j]; } }
;     }
	v_lshlrev_b32_e32 v40, 16, v140
	v_and_b32_e32 v41, 0xffff0000, v140
	v_lshlrev_b32_e32 v42, 16, v141
	v_and_b32_e32 v43, 0xffff0000, v141
	v_lshlrev_b32_e32 v44, 16, v142
	v_and_b32_e32 v45, 0xffff0000, v142
	v_lshlrev_b32_e32 v46, 16, v143
	v_and_b32_e32 v47, 0xffff0000, v143
	v_lshlrev_b32_e32 v48, 16, v144
	v_and_b32_e32 v49, 0xffff0000, v144
	v_lshlrev_b32_e32 v50, 16, v145
	v_and_b32_e32 v51, 0xffff0000, v145
	v_lshlrev_b32_e32 v52, 16, v146
	v_and_b32_e32 v53, 0xffff0000, v146
	v_lshlrev_b32_e32 v54, 16, v147
	v_and_b32_e32 v55, 0xffff0000, v147
	v_mul_f32_e32 v60, v41, v41
	v_fmac_f32_e32 v60, v40, v40
	v_mul_f32_e32 v61, v43, v43
	v_fmac_f32_e32 v61, v42, v42
	v_add_f32_e32 v62, v60, v61
	v_mul_f32_e32 v60, v45, v45
	v_fmac_f32_e32 v60, v44, v44
	v_mul_f32_e32 v61, v47, v47
	v_fmac_f32_e32 v61, v46, v46
	v_add_f32_e32 v60, v60, v61
	v_add_f32_e32 v62, v62, v60
	v_mul_f32_e32 v60, v49, v49
	v_fmac_f32_e32 v60, v48, v48
	v_mul_f32_e32 v61, v51, v51
	v_fmac_f32_e32 v61, v50, v50
	v_add_f32_e32 v60, v60, v61
	v_add_f32_e32 v62, v62, v60
	v_mul_f32_e32 v60, v53, v53
	v_fmac_f32_e32 v60, v52, v52
	v_mul_f32_e32 v61, v55, v55
	v_fmac_f32_e32 v61, v54, v54
	v_add_f32_e32 v60, v60, v61
	v_add_f32_e32 v62, v62, v60
	s_nop 1
	v_add_f32_dpp v62, v62, v62 quad_perm:[1,0,3,2] row_mask:0xf bank_mask:0xf
	s_nop 1
	v_add_f32_dpp v62, v62, v62 quad_perm:[2,3,0,1] row_mask:0xf bank_mask:0xf
	s_nop 1
	v_add_f32_dpp v62, v62, v62 row_half_mirror row_mask:0xf bank_mask:0xf
	s_nop 1
	v_add_f32_dpp v62, v62, v62 row_mirror row_mask:0xf bank_mask:0xf
	v_mov_b32_e32 v63, v62
	v_mov_b32_e32 v64, v62
	s_nop 1
	v_permlane16_swap_b32_e32 v63, v64
	v_add_f32_e32 v63, v63, v64
	v_mov_b32_e32 v64, v63
	s_nop 1
	v_permlane32_swap_b32_e32 v63, v64
	v_add_f32_e32 v62, v63, v64
	v_fmamk_f32 v62, v62, 0x3a800000, v1
	v_mul_f32_e32 v63, 0x4f800000, v62
	v_cmp_gt_f32_e32 vcc, s3, v62
	s_nop 1
	v_cndmask_b32_e32 v62, v62, v63, vcc
	v_sqrt_f32_e32 v63, v62
	s_nop 0
	v_add_u32_e32 v32, -1, v63
	v_add_u32_e32 v64, 1, v63
	v_fma_f32 v65, -v32, v63, v62
	v_fma_f32 v66, -v64, v63, v62
	v_cmp_ge_f32_e64 s[36:37], 0, v65
	s_nop 1
	v_cndmask_b32_e64 v32, v63, v32, s[36:37]
	v_cmp_lt_f32_e64 s[36:37], 0, v66
	s_nop 1
	v_cndmask_b32_e64 v32, v32, v64, s[36:37]
	v_mul_f32_e32 v63, 0x37800000, v32
	v_cndmask_b32_e32 v32, v32, v63, vcc
	v_cmp_class_f32_e32 vcc, v62, v210
	s_nop 1
	v_cndmask_b32_e32 v32, v32, v62, vcc
	v_div_scale_f32 v63, s[8:9], v32, v32, 1.0
	v_rcp_f32_e32 v64, v63
	v_div_scale_f32 v65, vcc, 1.0, v32, 1.0
	v_fma_f32 v66, -v63, v64, 1.0
	v_fmac_f32_e32 v64, v66, v64
	v_mul_f32_e32 v66, v65, v64
	v_fma_f32 v67, -v63, v66, v65
	v_fmac_f32_e32 v66, v67, v64
	v_fma_f32 v63, -v63, v66, v65
	s_nop 1
	v_div_fmas_f32 v63, v63, v64, v66
	v_div_fixup_f32 v68, v63, v32, 1.0
	v_mul_f32_e32 v40, v68, v40
	v_mul_f32_e32 v41, v68, v41
	v_mul_f32_e32 v42, v68, v42
	v_mul_f32_e32 v43, v68, v43
	v_mul_f32_e32 v40, v2, v40
	v_mul_f32_e32 v41, v3, v41
	v_mul_f32_e32 v42, v4, v42
	v_mul_f32_e32 v43, v5, v43
	global_store_dwordx4 v[24:25], v[40:43], off
	v_mul_f32_e32 v44, v68, v44
	v_mul_f32_e32 v45, v68, v45
	v_mul_f32_e32 v46, v68, v46
	v_mul_f32_e32 v47, v68, v47
	v_mul_f32_e32 v44, v6, v44
	v_mul_f32_e32 v45, v7, v45
	v_mul_f32_e32 v46, v8, v46
	v_mul_f32_e32 v47, v9, v47
	global_store_dwordx4 v[24:25], v[44:47], off offset:1024
	v_mul_f32_e32 v48, v68, v48
	v_mul_f32_e32 v49, v68, v49
	v_mul_f32_e32 v50, v68, v50
	v_mul_f32_e32 v51, v68, v51
	v_mul_f32_e32 v48, v10, v48
	v_mul_f32_e32 v49, v11, v49
	v_mul_f32_e32 v50, v12, v50
	v_mul_f32_e32 v51, v13, v51
	global_store_dwordx4 v[24:25], v[48:51], off offset:2048
	v_mul_f32_e32 v52, v68, v52
	v_mul_f32_e32 v53, v68, v53
	v_mul_f32_e32 v54, v68, v54
	v_mul_f32_e32 v55, v68, v55
	v_mul_f32_e32 v52, v14, v52
	v_mul_f32_e32 v53, v15, v53
	v_mul_f32_e32 v54, v16, v54
	v_mul_f32_e32 v55, v17, v55
	global_store_dwordx4 v[24:25], v[52:55], off offset:3072
	v_lshl_add_u64 v[24:25], v[24:25], 0, s[6:7]
	s_waitcnt vmcnt(28)
	v_lshlrev_b32_e32 v40, 16, v148
	v_and_b32_e32 v41, 0xffff0000, v148
	v_lshlrev_b32_e32 v42, 16, v149
	v_and_b32_e32 v43, 0xffff0000, v149
	v_lshlrev_b32_e32 v44, 16, v150
	v_and_b32_e32 v45, 0xffff0000, v150
	v_lshlrev_b32_e32 v46, 16, v151
	v_and_b32_e32 v47, 0xffff0000, v151
	v_lshlrev_b32_e32 v48, 16, v152
	v_and_b32_e32 v49, 0xffff0000, v152
	v_lshlrev_b32_e32 v50, 16, v153
	v_and_b32_e32 v51, 0xffff0000, v153
	v_lshlrev_b32_e32 v52, 16, v154
	v_and_b32_e32 v53, 0xffff0000, v154
	v_lshlrev_b32_e32 v54, 16, v155
	v_and_b32_e32 v55, 0xffff0000, v155
	v_mul_f32_e32 v60, v41, v41
	v_fmac_f32_e32 v60, v40, v40
	v_mul_f32_e32 v61, v43, v43
	v_fmac_f32_e32 v61, v42, v42
	v_add_f32_e32 v62, v60, v61
	v_mul_f32_e32 v60, v45, v45
	v_fmac_f32_e32 v60, v44, v44
	v_mul_f32_e32 v61, v47, v47
	v_fmac_f32_e32 v61, v46, v46
	v_add_f32_e32 v60, v60, v61
	v_add_f32_e32 v62, v62, v60
	v_mul_f32_e32 v60, v49, v49
	v_fmac_f32_e32 v60, v48, v48
	v_mul_f32_e32 v61, v51, v51
	v_fmac_f32_e32 v61, v50, v50
	v_add_f32_e32 v60, v60, v61
	v_add_f32_e32 v62, v62, v60
	v_mul_f32_e32 v60, v53, v53
	v_fmac_f32_e32 v60, v52, v52
	v_mul_f32_e32 v61, v55, v55
	v_fmac_f32_e32 v61, v54, v54
	v_add_f32_e32 v60, v60, v61
	v_add_f32_e32 v62, v62, v60
	s_nop 1
	v_add_f32_dpp v62, v62, v62 quad_perm:[1,0,3,2] row_mask:0xf bank_mask:0xf
	s_nop 1
	v_add_f32_dpp v62, v62, v62 quad_perm:[2,3,0,1] row_mask:0xf bank_mask:0xf
	s_nop 1
	v_add_f32_dpp v62, v62, v62 row_half_mirror row_mask:0xf bank_mask:0xf
	s_nop 1
	v_add_f32_dpp v62, v62, v62 row_mirror row_mask:0xf bank_mask:0xf
	v_mov_b32_e32 v63, v62
	v_mov_b32_e32 v64, v62
	s_nop 1
	v_permlane16_swap_b32_e32 v63, v64
; __device__ __forceinline__ f32x4 ld4bf(const bf16* p) { const v2u w = *(const v2u*)p; return (f32x4){bf_lo(w.x), bf_hi(w.x), bf_lo(w.y), bf_hi(w.y)}; }
; __device__ __forceinline__ void final_norm(const bf16* X, const float* g, float* out, int vcu, int G, int wave, int lane) {
;     ...
;     for (int m0 = gw; m0 < M; m0 += 2 * NGW) {
;         f32x4 v[2][4]; float rs[2];
; #pragma unroll
;         for (int u = 0; u < 2; ++u) { const int m = m0 + u * NGW; const bf16* xr = X + (size_t)(m < M ? m : m0) * DM + 4 * lane;
; #pragma unroll
;             for (int j = 0; j < 4; ++j) v[u][j] = ld4bf(xr + 256 * j); }
; #pragma unroll
;         for (int u = 0; u < 2; ++u) { float s = 0.f;
; #pragma unroll
;             for (int j = 0; j < 4; ++j) s += (v[u][j][0] * v[u][j][0] + v[u][j][1] * v[u][j][1]) + (v[u][j][2] * v[u][j][2] + v[u][j][3] * v[u][j][3]);
;             s = wave_sum(s); rs[u] = 1.0f / sqrtf(s * (1.0f / 1024.0f) + 1e-6f); }
; #pragma unroll
;         for (int u = 0; u < 2; ++u) { const int m = m0 + u * NGW; if (m < M) { f32x4* o = (f32x4*)(out + (size_t)m * DM) + lane;
; #pragma unroll
;             for (int j = 0; j < 4; ++j) o[64 * j] = v[u][j] * rs[u] * gv[j]; } }
;     }
	v_add_f32_e32 v63, v63, v64
	v_mov_b32_e32 v64, v63
	s_nop 1
	v_permlane32_swap_b32_e32 v63, v64
	v_add_f32_e32 v62, v63, v64
	v_fmamk_f32 v62, v62, 0x3a800000, v1
	v_mul_f32_e32 v63, 0x4f800000, v62
	v_cmp_gt_f32_e32 vcc, s3, v62
	s_nop 1
	v_cndmask_b32_e32 v62, v62, v63, vcc
	v_sqrt_f32_e32 v63, v62
	s_nop 0
	v_add_u32_e32 v32, -1, v63
	v_add_u32_e32 v64, 1, v63
	v_fma_f32 v65, -v32, v63, v62
	v_fma_f32 v66, -v64, v63, v62
	v_cmp_ge_f32_e64 s[36:37], 0, v65
	s_nop 1
	v_cndmask_b32_e64 v32, v63, v32, s[36:37]
	v_cmp_lt_f32_e64 s[36:37], 0, v66
	s_nop 1
	v_cndmask_b32_e64 v32, v32, v64, s[36:37]
	v_mul_f32_e32 v63, 0x37800000, v32
	v_cndmask_b32_e32 v32, v32, v63, vcc
	v_cmp_class_f32_e32 vcc, v62, v210
	s_nop 1
	v_cndmask_b32_e32 v32, v32, v62, vcc
	v_div_scale_f32 v63, s[8:9], v32, v32, 1.0
	v_rcp_f32_e32 v64, v63
	v_div_scale_f32 v65, vcc, 1.0, v32, 1.0
	v_fma_f32 v66, -v63, v64, 1.0
	v_fmac_f32_e32 v64, v66, v64
	v_mul_f32_e32 v66, v65, v64
	v_fma_f32 v67, -v63, v66, v65
	v_fmac_f32_e32 v66, v67, v64
	v_fma_f32 v63, -v63, v66, v65
	s_nop 1
	v_div_fmas_f32 v63, v63, v64, v66
	v_div_fixup_f32 v68, v63, v32, 1.0
	v_mul_f32_e32 v40, v68, v40
	v_mul_f32_e32 v41, v68, v41
	v_mul_f32_e32 v42, v68, v42
	v_mul_f32_e32 v43, v68, v43
	v_mul_f32_e32 v40, v2, v40
	v_mul_f32_e32 v41, v3, v41
	v_mul_f32_e32 v42, v4, v42
	v_mul_f32_e32 v43, v5, v43
	global_store_dwordx4 v[24:25], v[40:43], off
	v_mul_f32_e32 v44, v68, v44
	v_mul_f32_e32 v45, v68, v45
	v_mul_f32_e32 v46, v68, v46
	v_mul_f32_e32 v47, v68, v47
	v_mul_f32_e32 v44, v6, v44
	v_mul_f32_e32 v45, v7, v45
	v_mul_f32_e32 v46, v8, v46
	v_mul_f32_e32 v47, v9, v47
	global_store_dwordx4 v[24:25], v[44:47], off offset:1024
	v_mul_f32_e32 v48, v68, v48
	v_mul_f32_e32 v49, v68, v49
	v_mul_f32_e32 v50, v68, v50
	v_mul_f32_e32 v51, v68, v51
	v_mul_f32_e32 v48, v10, v48
	v_mul_f32_e32 v49, v11, v49
	v_mul_f32_e32 v50, v12, v50
	v_mul_f32_e32 v51, v13, v51
	global_store_dwordx4 v[24:25], v[48:51], off offset:2048
	v_mul_f32_e32 v52, v68, v52
	v_mul_f32_e32 v53, v68, v53
	v_mul_f32_e32 v54, v68, v54
	v_mul_f32_e32 v55, v68, v55
	v_mul_f32_e32 v52, v14, v52
	v_mul_f32_e32 v53, v15, v53
	v_mul_f32_e32 v54, v16, v54
	v_mul_f32_e32 v55, v17, v55
	global_store_dwordx4 v[24:25], v[52:55], off offset:3072
	v_lshl_add_u64 v[24:25], v[24:25], 0, s[6:7]
	s_waitcnt vmcnt(28)
	v_lshlrev_b32_e32 v40, 16, v156
	v_and_b32_e32 v41, 0xffff0000, v156
	v_lshlrev_b32_e32 v42, 16, v157
	v_and_b32_e32 v43, 0xffff0000, v157
	v_lshlrev_b32_e32 v44, 16, v158
	v_and_b32_e32 v45, 0xffff0000, v158
	v_lshlrev_b32_e32 v46, 16, v159
	v_and_b32_e32 v47, 0xffff0000, v159
	v_lshlrev_b32_e32 v48, 16, v160
	v_and_b32_e32 v49, 0xffff0000, v160
	v_lshlrev_b32_e32 v50, 16, v161
	v_and_b32_e32 v51, 0xffff0000, v161
	v_lshlrev_b32_e32 v52, 16, v162
	v_and_b32_e32 v53, 0xffff0000, v162
	v_lshlrev_b32_e32 v54, 16, v163
	v_and_b32_e32 v55, 0xffff0000, v163
	v_mul_f32_e32 v60, v41, v41
	v_fmac_f32_e32 v60, v40, v40
	v_mul_f32_e32 v61, v43, v43
	v_fmac_f32_e32 v61, v42, v42
	v_add_f32_e32 v62, v60, v61
	v_mul_f32_e32 v60, v45, v45
	v_fmac_f32_e32 v60, v44, v44
	v_mul_f32_e32 v61, v47, v47
	v_fmac_f32_e32 v61, v46, v46
	v_add_f32_e32 v60, v60, v61
	v_add_f32_e32 v62, v62, v60
	v_mul_f32_e32 v60, v49, v49
	v_fmac_f32_e32 v60, v48, v48
	v_mul_f32_e32 v61, v51, v51
	v_fmac_f32_e32 v61, v50, v50
	v_add_f32_e32 v60, v60, v61
	v_add_f32_e32 v62, v62, v60
	v_mul_f32_e32 v60, v53, v53
	v_fmac_f32_e32 v60, v52, v52
	v_mul_f32_e32 v61, v55, v55
	v_fmac_f32_e32 v61, v54, v54
	v_add_f32_e32 v60, v60, v61
	v_add_f32_e32 v62, v62, v60
	s_nop 1
	v_add_f32_dpp v62, v62, v62 quad_perm:[1,0,3,2] row_mask:0xf bank_mask:0xf
	s_nop 1
	v_add_f32_dpp v62, v62, v62 quad_perm:[2,3,0,1] row_mask:0xf bank_mask:0xf
	s_nop 1
	v_add_f32_dpp v62, v62, v62 row_half_mirror row_mask:0xf bank_mask:0xf
	s_nop 1
	v_add_f32_dpp v62, v62, v62 row_mirror row_mask:0xf bank_mask:0xf
	v_mov_b32_e32 v63, v62
	v_mov_b32_e32 v64, v62
	s_nop 1
	v_permlane16_swap_b32_e32 v63, v64
	v_add_f32_e32 v63, v63, v64
	v_mov_b32_e32 v64, v63
	s_nop 1
	v_permlane32_swap_b32_e32 v63, v64
	v_add_f32_e32 v62, v63, v64
	v_fmamk_f32 v62, v62, 0x3a800000, v1
	v_mul_f32_e32 v63, 0x4f800000, v62
	v_cmp_gt_f32_e32 vcc, s3, v62
	s_nop 1
	v_cndmask_b32_e32 v62, v62, v63, vcc
	v_sqrt_f32_e32 v63, v62
	s_nop 0
	v_add_u32_e32 v32, -1, v63
	v_add_u32_e32 v64, 1, v63
	v_fma_f32 v65, -v32, v63, v62
	v_fma_f32 v66, -v64, v63, v62
	v_cmp_ge_f32_e64 s[36:37], 0, v65
	s_nop 1
	v_cndmask_b32_e64 v32, v63, v32, s[36:37]
	v_cmp_lt_f32_e64 s[36:37], 0, v66
	s_nop 1
	v_cndmask_b32_e64 v32, v32, v64, s[36:37]
	v_mul_f32_e32 v63, 0x37800000, v32
	v_cndmask_b32_e32 v32, v32, v63, vcc
	v_cmp_class_f32_e32 vcc, v62, v210
	s_nop 1
	v_cndmask_b32_e32 v32, v32, v62, vcc
	v_div_scale_f32 v63, s[8:9], v32, v32, 1.0
	v_rcp_f32_e32 v64, v63
	v_div_scale_f32 v65, vcc, 1.0, v32, 1.0
	v_fma_f32 v66, -v63, v64, 1.0
	v_fmac_f32_e32 v64, v66, v64
	v_mul_f32_e32 v66, v65, v64
	v_fma_f32 v67, -v63, v66, v65
	v_fmac_f32_e32 v66, v67, v64
	v_fma_f32 v63, -v63, v66, v65
	s_nop 1
	v_div_fmas_f32 v63, v63, v64, v66
	v_div_fixup_f32 v68, v63, v32, 1.0
	v_mul_f32_e32 v40, v68, v40
	v_mul_f32_e32 v41, v68, v41
	v_mul_f32_e32 v42, v68, v42
	v_mul_f32_e32 v43, v68, v43
	v_mul_f32_e32 v40, v2, v40
	v_mul_f32_e32 v41, v3, v41
	v_mul_f32_e32 v42, v4, v42
	v_mul_f32_e32 v43, v5, v43
	global_store_dwordx4 v[24:25], v[40:43], off
	v_mul_f32_e32 v44, v68, v44
	v_mul_f32_e32 v45, v68, v45
	v_mul_f32_e32 v46, v68, v46
	v_mul_f32_e32 v47, v68, v47
	v_mul_f32_e32 v44, v6, v44
	v_mul_f32_e32 v45, v7, v45
	v_mul_f32_e32 v46, v8, v46
	v_mul_f32_e32 v47, v9, v47
	global_store_dwordx4 v[24:25], v[44:47], off offset:1024
	v_mul_f32_e32 v48, v68, v48
	v_mul_f32_e32 v49, v68, v49
	v_mul_f32_e32 v50, v68, v50
	v_mul_f32_e32 v51, v68, v51
	v_mul_f32_e32 v48, v10, v48
	v_mul_f32_e32 v49, v11, v49
	v_mul_f32_e32 v50, v12, v50
	v_mul_f32_e32 v51, v13, v51
	global_store_dwordx4 v[24:25], v[48:51], off offset:2048
	v_mul_f32_e32 v52, v68, v52
	v_mul_f32_e32 v53, v68, v53
	v_mul_f32_e32 v54, v68, v54
	v_mul_f32_e32 v55, v68, v55
	v_mul_f32_e32 v52, v14, v52
	v_mul_f32_e32 v53, v15, v53
	v_mul_f32_e32 v54, v16, v54
	v_mul_f32_e32 v55, v17, v55
	global_store_dwordx4 v[24:25], v[52:55], off offset:3072
	s_branch .LBB0_19
	s_branch .LBB0_17

; __device__ __forceinline__ f32x4 ld4bf(const bf16* p) { const v2u w = *(const v2u*)p; return (f32x4){bf_lo(w.x), bf_hi(w.x), bf_lo(w.y), bf_hi(w.y)}; }
; __device__ __forceinline__ void pool_prep(const bf16* X, const float* ss, const float* gain, bf16* PB, LAS unsigned char* lds, int vcu, int G, int tid) {
;     ...
;     for (int chunk = vcu; chunk < M / 64; chunk += G) {
;         const int r0 = chunk * 64, bstart = r0 & ~(SEQ - 1);
;         __syncthreads();
;         if (tid < 80) { const int row = r0 - 16 + tid; rsl[tid] = (row >= bstart) ? pg8::row_rstd(ss, row) : 0.f; }
;         __syncthreads();
;         const int q = tid & 255, half = tid >> 8, w = 2 << (q >> 6);
;         const f32x4 gn = *(const f32x4*)(gain + 4 * q);
;         const int ra = r0 + 32 * half;
;         const bf16* xp = X + 4 * q;
;         f32x4 S = {0.f, 0.f, 0.f, 0.f};
; #pragma unroll
;         for (int j = 1; j <= 16; ++j) { const int row = ra - j; if (j <= w && row >= bstart) S += ld4bf(xp + (size_t)row * DM) * rsl[row - r0 + 16]; }
.Lmy_pool_w2:
	s_mov_b32 s0, 4096
	v_subrev_co_u32_e32 v198, vcc, s0, v22
	s_nop 1
	v_subbrev_co_u32_e32 v199, vcc, 0, v23, vcc
	s_mov_b64 s[0:1], 0x1000
	global_load_dwordx2 v[100:101], v[198:199], off
	global_load_dwordx2 v[102:103], v[198:199], off offset:2048
	v_lshl_add_u64 v[198:199], v[198:199], 0, s[0:1]
	global_load_dwordx2 v[104:105], v[198:199], off
	global_load_dwordx2 v[106:107], v[198:199], off offset:2048
	v_lshl_add_u64 v[198:199], v[198:199], 0, s[0:1]
	global_load_dwordx2 v[108:109], v[198:199], off
	global_load_dwordx2 v[110:111], v[198:199], off offset:2048
	v_lshl_add_u64 v[198:199], v[198:199], 0, s[0:1]
	global_load_dwordx2 v[112:113], v[198:199], off
	global_load_dwordx2 v[114:115], v[198:199], off offset:2048
	v_lshl_add_u64 v[198:199], v[198:199], 0, s[0:1]
	global_load_dwordx2 v[116:117], v[198:199], off
	global_load_dwordx2 v[118:119], v[198:199], off offset:2048
	v_lshl_add_u64 v[198:199], v[198:199], 0, s[0:1]
	global_load_dwordx2 v[120:121], v[198:199], off
	global_load_dwordx2 v[122:123], v[198:199], off offset:2048
	v_lshl_add_u64 v[198:199], v[198:199], 0, s[0:1]
	global_load_dwordx2 v[124:125], v[198:199], off
	global_load_dwordx2 v[126:127], v[198:199], off offset:2048
	v_lshl_add_u64 v[198:199], v[198:199], 0, s[0:1]
	global_load_dwordx2 v[128:129], v[198:199], off
	global_load_dwordx2 v[130:131], v[198:199], off offset:2048
	v_lshl_add_u64 v[198:199], v[198:199], 0, s[0:1]
	global_load_dwordx2 v[132:133], v[198:199], off
	global_load_dwordx2 v[134:135], v[198:199], off offset:2048
	v_lshl_add_u64 v[198:199], v[198:199], 0, s[0:1]
	global_load_dwordx2 v[136:137], v[198:199], off
	global_load_dwordx2 v[138:139], v[198:199], off offset:2048
	v_lshl_add_u64 v[198:199], v[198:199], 0, s[0:1]
	global_load_dwordx2 v[140:141], v[198:199], off
	global_load_dwordx2 v[142:143], v[198:199], off offset:2048
	v_lshl_add_u64 v[198:199], v[198:199], 0, s[0:1]
	global_load_dwordx2 v[144:145], v[198:199], off
	global_load_dwordx2 v[146:147], v[198:199], off offset:2048
	v_lshl_add_u64 v[198:199], v[198:199], 0, s[0:1]
	global_load_dwordx2 v[148:149], v[198:199], off
	global_load_dwordx2 v[150:151], v[198:199], off offset:2048
	v_lshl_add_u64 v[198:199], v[198:199], 0, s[0:1]
	global_load_dwordx2 v[152:153], v[198:199], off
	global_load_dwordx2 v[154:155], v[198:199], off offset:2048
	v_lshl_add_u64 v[198:199], v[198:199], 0, s[0:1]
	global_load_dwordx2 v[156:157], v[198:199], off
	global_load_dwordx2 v[158:159], v[198:199], off offset:2048
	v_lshl_add_u64 v[198:199], v[198:199], 0, s[0:1]
	global_load_dwordx2 v[160:161], v[198:199], off
	global_load_dwordx2 v[162:163], v[198:199], off offset:2048
	v_lshl_add_u64 v[198:199], v[198:199], 0, s[0:1]
	global_load_dwordx2 v[164:165], v[198:199], off
	global_load_dwordx2 v[166:167], v[198:199], off offset:2048
	ds_read_b32 v40, v21 offset:56
	ds_read_b32 v41, v21 offset:60
	ds_read_b32 v42, v21 offset:64
	ds_read_b32 v43, v21 offset:68
	ds_read_b32 v44, v21 offset:72
	ds_read_b32 v45, v21 offset:76
	ds_read_b32 v46, v21 offset:80
	ds_read_b32 v47, v21 offset:84
	ds_read_b32 v48, v21 offset:88
	ds_read_b32 v49, v21 offset:92
	ds_read_b32 v50, v21 offset:96
	ds_read_b32 v51, v21 offset:100
	s_waitcnt lgkmcnt(0)
	ds_read_b32 v52, v21 offset:104
	ds_read_b32 v53, v21 offset:108
	ds_read_b32 v54, v21 offset:112
	ds_read_b32 v55, v21 offset:116
	ds_read_b32 v56, v21 offset:120
	ds_read_b32 v57, v21 offset:124
	ds_read_b32 v58, v21 offset:128
	ds_read_b32 v59, v21 offset:132
	ds_read_b32 v60, v21 offset:136
	ds_read_b32 v61, v21 offset:140
	ds_read_b32 v62, v21 offset:144
	ds_read_b32 v63, v21 offset:148
	s_waitcnt lgkmcnt(0)
	ds_read_b32 v64, v21 offset:152
	ds_read_b32 v65, v21 offset:156
	ds_read_b32 v66, v21 offset:160
	ds_read_b32 v67, v21 offset:164
	ds_read_b32 v68, v21 offset:168
	ds_read_b32 v69, v21 offset:172
	ds_read_b32 v70, v21 offset:176
	ds_read_b32 v71, v21 offset:180
	ds_read_b32 v72, v21 offset:184
	ds_read_b32 v73, v21 offset:188
	v_div_scale_f32 v26, s[0:1], v196, v196, 1.0
	v_rcp_f32_e32 v27, v26
	s_nop 0
	v_fma_f32 v28, -v26, v27, 1.0
	v_fmac_f32_e32 v27, v28, v27
	v_div_scale_f32 v28, vcc, 1.0, v196, 1.0
	v_mul_f32_e32 v29, v28, v27
	v_fma_f32 v30, -v26, v29, v28
	v_fmac_f32_e32 v29, v30, v27
	v_fma_f32 v26, -v26, v29, v28
	s_nop 1
	v_div_fmas_f32 v197, v26, v27, v29
	v_div_fixup_f32 v197, v197, v196, 1.0
	v_mov_b32_e32 v6, 0
	v_mov_b32_e32 v7, 0
	v_mov_b32_e32 v8, 0
	v_mov_b32_e32 v9, 0
	s_waitcnt lgkmcnt(0)
	s_waitcnt vmcnt(32)
	v_cndmask_b32_e64 v100, v100, 0, s[6:7]
	v_cndmask_b32_e64 v101, v101, 0, s[6:7]
	v_cndmask_b32_e64 v102, v102, 0, s[6:7]
	v_cndmask_b32_e64 v103, v103, 0, s[6:7]
	v_lshlrev_b32_e32 v200, 16, v102
	v_and_b32_e32 v201, 0xffff0000, v102
	v_lshlrev_b32_e32 v202, 16, v103
	v_and_b32_e32 v203, 0xffff0000, v103
	v_fma_f32 v6, v41, v200, v6
	v_fma_f32 v7, v41, v201, v7
	v_fma_f32 v8, v41, v202, v8
	v_fma_f32 v9, v41, v203, v9
	v_lshlrev_b32_e32 v200, 16, v100
	v_and_b32_e32 v201, 0xffff0000, v100
	v_lshlrev_b32_e32 v202, 16, v101
	v_and_b32_e32 v203, 0xffff0000, v101
	v_fma_f32 v6, v40, v200, v6
	v_fma_f32 v7, v40, v201, v7
	v_fma_f32 v8, v40, v202, v8
	v_fma_f32 v9, v40, v203, v9
	s_waitcnt vmcnt(31)
; __device__ __forceinline__ unsigned pk2(float lo, float hi) { return pg8::cvt_pk_bf16(lo, hi); }
; __device__ __forceinline__ f32x4 ld4bf(const bf16* p) { const v2u w = *(const v2u*)p; return (f32x4){bf_lo(w.x), bf_hi(w.x), bf_lo(w.y), bf_hi(w.y)}; }
; __device__ __forceinline__ void pool_prep(const bf16* X, const float* ss, const float* gain, bf16* PB, LAS unsigned char* lds, int vcu, int G, int tid) {
;     ...
;         for (int i = 0; i < 32; ++i) { const int row = ra + i, t = row - bstart;
;             const f32x4 xn = ld4bf(xp + (size_t)row * DM) * rsl[row - r0 + 16];
;             f32x4 old = {0.f, 0.f, 0.f, 0.f};
;             if (t >= w) old = ld4bf(xp + (size_t)(row - w) * DM) * rsl[row - w - r0 + 16];
;             S = S + xn - old;
;             const int cnt = (t + 1 < w) ? t + 1 : w;
;             const f32x4 p = (S * (1.0f / (float)cnt) - xn) * gn;
;             v2u o; o.x = pk2(p[0], p[1]); o.y = pk2(p[2], p[3]); *(v2u*)(PB + (size_t)row * DM + 4 * q) = o; }
	v_lshlrev_b32_e32 v200, 16, v104
	v_and_b32_e32 v201, 0xffff0000, v104
	v_lshlrev_b32_e32 v202, 16, v105
	v_and_b32_e32 v203, 0xffff0000, v105
	v_mul_f32_e32 v204, v42, v200
	v_mul_f32_e32 v205, v42, v201
	v_mul_f32_e32 v206, v42, v202
	v_mul_f32_e32 v207, v42, v203
	v_fma_f32 v6, v42, v200, v6
	v_fma_f32 v7, v42, v201, v7
	v_fma_f32 v8, v42, v202, v8
	v_fma_f32 v9, v42, v203, v9
	v_lshlrev_b32_e32 v88, 16, v100
	v_and_b32_e32 v89, 0xffff0000, v100
	v_lshlrev_b32_e32 v90, 16, v101
	v_and_b32_e32 v91, 0xffff0000, v101
	v_mul_f32_e32 v88, v40, v88
	v_mul_f32_e32 v89, v40, v89
	v_mul_f32_e32 v90, v40, v90
	v_mul_f32_e32 v91, v40, v91
	v_sub_f32_e32 v6, v6, v88
	v_sub_f32_e32 v7, v7, v89
	v_sub_f32_e32 v8, v8, v90
	v_sub_f32_e32 v9, v9, v91
	v_add_u32_e32 v92, 1, v20
	v_min_i32_e32 v92, v92, v32
	v_cvt_f32_i32_e32 v92, v92
	v_div_scale_f32 v26, s[0:1], v92, v92, 1.0
	v_rcp_f32_e32 v27, v26
	s_nop 0
	v_fma_f32 v28, -v26, v27, 1.0
	v_fmac_f32_e32 v27, v28, v27
	v_div_scale_f32 v28, vcc, 1.0, v92, 1.0
	v_mul_f32_e32 v29, v28, v27
	v_fma_f32 v30, -v26, v29, v28
	v_fmac_f32_e32 v29, v30, v27
	v_fma_f32 v26, -v26, v29, v28
	s_nop 1
	v_div_fmas_f32 v93, v26, v27, v29
	v_div_fixup_f32 v93, v93, v92, 1.0
	v_fma_f32 v214, v93, v6, -v204
	v_fma_f32 v215, v93, v7, -v205
	v_fma_f32 v216, v93, v8, -v206
	v_fma_f32 v217, v93, v9, -v207
	v_mul_f32_e32 v214, v2, v214
	v_mul_f32_e32 v215, v3, v215
	v_mul_f32_e32 v216, v4, v216
	v_mul_f32_e32 v217, v5, v217
	v_cvt_pk_bf16_f32 v218, v214, v215
	v_cvt_pk_bf16_f32 v219, v216, v217
	global_store_dwordx2 v[24:25], v[218:219], off sc1
	s_waitcnt vmcnt(31)
	v_lshlrev_b32_e32 v200, 16, v106
	v_and_b32_e32 v201, 0xffff0000, v106
	v_lshlrev_b32_e32 v202, 16, v107
	v_and_b32_e32 v203, 0xffff0000, v107
	v_mul_f32_e32 v204, v43, v200
	v_mul_f32_e32 v205, v43, v201
	v_mul_f32_e32 v206, v43, v202
	v_mul_f32_e32 v207, v43, v203
	v_fma_f32 v6, v43, v200, v6
	v_fma_f32 v7, v43, v201, v7
	v_fma_f32 v8, v43, v202, v8
	v_fma_f32 v9, v43, v203, v9
	v_lshlrev_b32_e32 v88, 16, v102
	v_and_b32_e32 v89, 0xffff0000, v102
	v_lshlrev_b32_e32 v90, 16, v103
	v_and_b32_e32 v91, 0xffff0000, v103
	v_mul_f32_e32 v88, v41, v88
	v_mul_f32_e32 v89, v41, v89
	v_mul_f32_e32 v90, v41, v90
	v_mul_f32_e32 v91, v41, v91
	v_sub_f32_e32 v6, v6, v88
	v_sub_f32_e32 v7, v7, v89
	v_sub_f32_e32 v8, v8, v90
	v_sub_f32_e32 v9, v9, v91
	v_fma_f32 v214, v197, v6, -v204
	v_fma_f32 v215, v197, v7, -v205
	v_fma_f32 v216, v197, v8, -v206
	v_fma_f32 v217, v197, v9, -v207
	v_mul_f32_e32 v214, v2, v214
	v_mul_f32_e32 v215, v3, v215
	v_mul_f32_e32 v216, v4, v216
	v_mul_f32_e32 v217, v5, v217
	v_cvt_pk_bf16_f32 v218, v214, v215
	v_cvt_pk_bf16_f32 v219, v216, v217
	global_store_dwordx2 v[24:25], v[218:219], off offset:2048 sc1
	s_mov_b64 s[0:1], 0x1000
	v_lshl_add_u64 v[24:25], v[24:25], 0, s[0:1]
	s_waitcnt vmcnt(31)
	v_lshlrev_b32_e32 v200, 16, v108
	v_and_b32_e32 v201, 0xffff0000, v108
	v_lshlrev_b32_e32 v202, 16, v109
	v_and_b32_e32 v203, 0xffff0000, v109
	v_mul_f32_e32 v204, v44, v200
	v_mul_f32_e32 v205, v44, v201
	v_mul_f32_e32 v206, v44, v202
	v_mul_f32_e32 v207, v44, v203
	v_fma_f32 v6, v44, v200, v6
	v_fma_f32 v7, v44, v201, v7
	v_fma_f32 v8, v44, v202, v8
	v_fma_f32 v9, v44, v203, v9
	v_lshlrev_b32_e32 v88, 16, v104
	v_and_b32_e32 v89, 0xffff0000, v104
	v_lshlrev_b32_e32 v90, 16, v105
	v_and_b32_e32 v91, 0xffff0000, v105
	v_mul_f32_e32 v88, v42, v88
	v_mul_f32_e32 v89, v42, v89
	v_mul_f32_e32 v90, v42, v90
	v_mul_f32_e32 v91, v42, v91
	v_sub_f32_e32 v6, v6, v88
	v_sub_f32_e32 v7, v7, v89
	v_sub_f32_e32 v8, v8, v90
	v_sub_f32_e32 v9, v9, v91
	v_fma_f32 v214, v197, v6, -v204
	v_fma_f32 v215, v197, v7, -v205
	v_fma_f32 v216, v197, v8, -v206
	v_fma_f32 v217, v197, v9, -v207
	v_mul_f32_e32 v214, v2, v214
	v_mul_f32_e32 v215, v3, v215
	v_mul_f32_e32 v216, v4, v216
	v_mul_f32_e32 v217, v5, v217
	v_cvt_pk_bf16_f32 v218, v214, v215
	v_cvt_pk_bf16_f32 v219, v216, v217
	global_store_dwordx2 v[24:25], v[218:219], off sc1
	s_waitcnt vmcnt(31)
	v_lshlrev_b32_e32 v200, 16, v110
	v_and_b32_e32 v201, 0xffff0000, v110
	v_lshlrev_b32_e32 v202, 16, v111
	v_and_b32_e32 v203, 0xffff0000, v111
	v_mul_f32_e32 v204, v45, v200
	v_mul_f32_e32 v205, v45, v201
	v_mul_f32_e32 v206, v45, v202
	v_mul_f32_e32 v207, v45, v203
	v_fma_f32 v6, v45, v200, v6
	v_fma_f32 v7, v45, v201, v7
	v_fma_f32 v8, v45, v202, v8
	v_fma_f32 v9, v45, v203, v9
	v_lshlrev_b32_e32 v88, 16, v106
	v_and_b32_e32 v89, 0xffff0000, v106
	v_lshlrev_b32_e32 v90, 16, v107
	v_and_b32_e32 v91, 0xffff0000, v107
	v_mul_f32_e32 v88, v43, v88
	v_mul_f32_e32 v89, v43, v89
	v_mul_f32_e32 v90, v43, v90
	v_mul_f32_e32 v91, v43, v91
	v_sub_f32_e32 v6, v6, v88
	v_sub_f32_e32 v7, v7, v89
	v_sub_f32_e32 v8, v8, v90
	v_sub_f32_e32 v9, v9, v91
	v_fma_f32 v214, v197, v6, -v204
	v_fma_f32 v215, v197, v7, -v205
	v_fma_f32 v216, v197, v8, -v206
	v_fma_f32 v217, v197, v9, -v207
	v_mul_f32_e32 v214, v2, v214
	v_mul_f32_e32 v215, v3, v215
	v_mul_f32_e32 v216, v4, v216
	v_mul_f32_e32 v217, v5, v217
	v_cvt_pk_bf16_f32 v218, v214, v215
	v_cvt_pk_bf16_f32 v219, v216, v217
	global_store_dwordx2 v[24:25], v[218:219], off offset:2048 sc1
	s_mov_b64 s[0:1], 0x1000
	v_lshl_add_u64 v[24:25], v[24:25], 0, s[0:1]
	s_waitcnt vmcnt(31)
; __device__ __forceinline__ unsigned pk2(float lo, float hi) { return pg8::cvt_pk_bf16(lo, hi); }
; __device__ __forceinline__ f32x4 ld4bf(const bf16* p) { const v2u w = *(const v2u*)p; return (f32x4){bf_lo(w.x), bf_hi(w.x), bf_lo(w.y), bf_hi(w.y)}; }
; __device__ __forceinline__ void pool_prep(const bf16* X, const float* ss, const float* gain, bf16* PB, LAS unsigned char* lds, int vcu, int G, int tid) {
;     ...
;         for (int i = 0; i < 32; ++i) { const int row = ra + i, t = row - bstart;
;             const f32x4 xn = ld4bf(xp + (size_t)row * DM) * rsl[row - r0 + 16];
;             f32x4 old = {0.f, 0.f, 0.f, 0.f};
;             if (t >= w) old = ld4bf(xp + (size_t)(row - w) * DM) * rsl[row - w - r0 + 16];
;             S = S + xn - old;
;             const int cnt = (t + 1 < w) ? t + 1 : w;
;             const f32x4 p = (S * (1.0f / (float)cnt) - xn) * gn;
;             v2u o; o.x = pk2(p[0], p[1]); o.y = pk2(p[2], p[3]); *(v2u*)(PB + (size_t)row * DM + 4 * q) = o; }
	v_lshlrev_b32_e32 v200, 16, v112
	v_and_b32_e32 v201, 0xffff0000, v112
	v_lshlrev_b32_e32 v202, 16, v113
	v_and_b32_e32 v203, 0xffff0000, v113
	v_mul_f32_e32 v204, v46, v200
	v_mul_f32_e32 v205, v46, v201
	v_mul_f32_e32 v206, v46, v202
	v_mul_f32_e32 v207, v46, v203
	v_fma_f32 v6, v46, v200, v6
	v_fma_f32 v7, v46, v201, v7
	v_fma_f32 v8, v46, v202, v8
	v_fma_f32 v9, v46, v203, v9
	v_lshlrev_b32_e32 v88, 16, v108
	v_and_b32_e32 v89, 0xffff0000, v108
	v_lshlrev_b32_e32 v90, 16, v109
	v_and_b32_e32 v91, 0xffff0000, v109
	v_mul_f32_e32 v88, v44, v88
	v_mul_f32_e32 v89, v44, v89
	v_mul_f32_e32 v90, v44, v90
	v_mul_f32_e32 v91, v44, v91
	v_sub_f32_e32 v6, v6, v88
	v_sub_f32_e32 v7, v7, v89
	v_sub_f32_e32 v8, v8, v90
	v_sub_f32_e32 v9, v9, v91
	v_fma_f32 v214, v197, v6, -v204
	v_fma_f32 v215, v197, v7, -v205
	v_fma_f32 v216, v197, v8, -v206
	v_fma_f32 v217, v197, v9, -v207
	v_mul_f32_e32 v214, v2, v214
	v_mul_f32_e32 v215, v3, v215
	v_mul_f32_e32 v216, v4, v216
	v_mul_f32_e32 v217, v5, v217
	v_cvt_pk_bf16_f32 v218, v214, v215
	v_cvt_pk_bf16_f32 v219, v216, v217
	global_store_dwordx2 v[24:25], v[218:219], off sc1
	s_waitcnt vmcnt(31)
	v_lshlrev_b32_e32 v200, 16, v114
	v_and_b32_e32 v201, 0xffff0000, v114
	v_lshlrev_b32_e32 v202, 16, v115
	v_and_b32_e32 v203, 0xffff0000, v115
	v_mul_f32_e32 v204, v47, v200
	v_mul_f32_e32 v205, v47, v201
	v_mul_f32_e32 v206, v47, v202
	v_mul_f32_e32 v207, v47, v203
	v_fma_f32 v6, v47, v200, v6
	v_fma_f32 v7, v47, v201, v7
	v_fma_f32 v8, v47, v202, v8
	v_fma_f32 v9, v47, v203, v9
	v_lshlrev_b32_e32 v88, 16, v110
	v_and_b32_e32 v89, 0xffff0000, v110
	v_lshlrev_b32_e32 v90, 16, v111
	v_and_b32_e32 v91, 0xffff0000, v111
	v_mul_f32_e32 v88, v45, v88
	v_mul_f32_e32 v89, v45, v89
	v_mul_f32_e32 v90, v45, v90
	v_mul_f32_e32 v91, v45, v91
	v_sub_f32_e32 v6, v6, v88
	v_sub_f32_e32 v7, v7, v89
	v_sub_f32_e32 v8, v8, v90
	v_sub_f32_e32 v9, v9, v91
	v_fma_f32 v214, v197, v6, -v204
	v_fma_f32 v215, v197, v7, -v205
	v_fma_f32 v216, v197, v8, -v206
	v_fma_f32 v217, v197, v9, -v207
	v_mul_f32_e32 v214, v2, v214
	v_mul_f32_e32 v215, v3, v215
	v_mul_f32_e32 v216, v4, v216
	v_mul_f32_e32 v217, v5, v217
	v_cvt_pk_bf16_f32 v218, v214, v215
	v_cvt_pk_bf16_f32 v219, v216, v217
	global_store_dwordx2 v[24:25], v[218:219], off offset:2048 sc1
	s_mov_b64 s[0:1], 0x1000
	v_lshl_add_u64 v[24:25], v[24:25], 0, s[0:1]
	s_waitcnt vmcnt(31)
	v_lshlrev_b32_e32 v200, 16, v116
	v_and_b32_e32 v201, 0xffff0000, v116
	v_lshlrev_b32_e32 v202, 16, v117
	v_and_b32_e32 v203, 0xffff0000, v117
	v_mul_f32_e32 v204, v48, v200
	v_mul_f32_e32 v205, v48, v201
	v_mul_f32_e32 v206, v48, v202
	v_mul_f32_e32 v207, v48, v203
	v_fma_f32 v6, v48, v200, v6
	v_fma_f32 v7, v48, v201, v7
	v_fma_f32 v8, v48, v202, v8
	v_fma_f32 v9, v48, v203, v9
	v_lshlrev_b32_e32 v88, 16, v112
	v_and_b32_e32 v89, 0xffff0000, v112
	v_lshlrev_b32_e32 v90, 16, v113
	v_and_b32_e32 v91, 0xffff0000, v113
	v_mul_f32_e32 v88, v46, v88
	v_mul_f32_e32 v89, v46, v89
	v_mul_f32_e32 v90, v46, v90
	v_mul_f32_e32 v91, v46, v91
	v_sub_f32_e32 v6, v6, v88
	v_sub_f32_e32 v7, v7, v89
	v_sub_f32_e32 v8, v8, v90
	v_sub_f32_e32 v9, v9, v91
	v_fma_f32 v214, v197, v6, -v204
	v_fma_f32 v215, v197, v7, -v205
	v_fma_f32 v216, v197, v8, -v206
	v_fma_f32 v217, v197, v9, -v207
	v_mul_f32_e32 v214, v2, v214
	v_mul_f32_e32 v215, v3, v215
	v_mul_f32_e32 v216, v4, v216
	v_mul_f32_e32 v217, v5, v217
	v_cvt_pk_bf16_f32 v218, v214, v215
	v_cvt_pk_bf16_f32 v219, v216, v217
	global_store_dwordx2 v[24:25], v[218:219], off sc1
	s_waitcnt vmcnt(31)
	v_lshlrev_b32_e32 v200, 16, v118
	v_and_b32_e32 v201, 0xffff0000, v118
	v_lshlrev_b32_e32 v202, 16, v119
	v_and_b32_e32 v203, 0xffff0000, v119
	v_mul_f32_e32 v204, v49, v200
	v_mul_f32_e32 v205, v49, v201
	v_mul_f32_e32 v206, v49, v202
	v_mul_f32_e32 v207, v49, v203
	v_fma_f32 v6, v49, v200, v6
	v_fma_f32 v7, v49, v201, v7
	v_fma_f32 v8, v49, v202, v8
	v_fma_f32 v9, v49, v203, v9
	v_lshlrev_b32_e32 v88, 16, v114
	v_and_b32_e32 v89, 0xffff0000, v114
	v_lshlrev_b32_e32 v90, 16, v115
	v_and_b32_e32 v91, 0xffff0000, v115
	v_mul_f32_e32 v88, v47, v88
	v_mul_f32_e32 v89, v47, v89
	v_mul_f32_e32 v90, v47, v90
	v_mul_f32_e32 v91, v47, v91
	v_sub_f32_e32 v6, v6, v88
	v_sub_f32_e32 v7, v7, v89
	v_sub_f32_e32 v8, v8, v90
	v_sub_f32_e32 v9, v9, v91
	v_fma_f32 v214, v197, v6, -v204
	v_fma_f32 v215, v197, v7, -v205
	v_fma_f32 v216, v197, v8, -v206
	v_fma_f32 v217, v197, v9, -v207
	v_mul_f32_e32 v214, v2, v214
	v_mul_f32_e32 v215, v3, v215
	v_mul_f32_e32 v216, v4, v216
	v_mul_f32_e32 v217, v5, v217
	v_cvt_pk_bf16_f32 v218, v214, v215
	v_cvt_pk_bf16_f32 v219, v216, v217
	global_store_dwordx2 v[24:25], v[218:219], off offset:2048 sc1
	s_mov_b64 s[0:1], 0x1000
	v_lshl_add_u64 v[24:25], v[24:25], 0, s[0:1]
	s_waitcnt vmcnt(31)
	v_lshlrev_b32_e32 v200, 16, v120
	v_and_b32_e32 v201, 0xffff0000, v120
	v_lshlrev_b32_e32 v202, 16, v121
	v_and_b32_e32 v203, 0xffff0000, v121
	v_mul_f32_e32 v204, v50, v200
	v_mul_f32_e32 v205, v50, v201
	v_mul_f32_e32 v206, v50, v202
	v_mul_f32_e32 v207, v50, v203
	v_fma_f32 v6, v50, v200, v6
	v_fma_f32 v7, v50, v201, v7
	v_fma_f32 v8, v50, v202, v8
	v_fma_f32 v9, v50, v203, v9
	v_lshlrev_b32_e32 v88, 16, v116
	v_and_b32_e32 v89, 0xffff0000, v116
	v_lshlrev_b32_e32 v90, 16, v117
	v_and_b32_e32 v91, 0xffff0000, v117
	v_mul_f32_e32 v88, v48, v88
	v_mul_f32_e32 v89, v48, v89
	v_mul_f32_e32 v90, v48, v90
	v_mul_f32_e32 v91, v48, v91
	v_sub_f32_e32 v6, v6, v88
	v_sub_f32_e32 v7, v7, v89
	v_sub_f32_e32 v8, v8, v90
	v_sub_f32_e32 v9, v9, v91
	v_fma_f32 v214, v197, v6, -v204
	v_fma_f32 v215, v197, v7, -v205
	v_fma_f32 v216, v197, v8, -v206
	v_fma_f32 v217, v197, v9, -v207
	v_mul_f32_e32 v214, v2, v214
	v_mul_f32_e32 v215, v3, v215
	v_mul_f32_e32 v216, v4, v216
	v_mul_f32_e32 v217, v5, v217
	v_cvt_pk_bf16_f32 v218, v214, v215
	v_cvt_pk_bf16_f32 v219, v216, v217
	global_store_dwordx2 v[24:25], v[218:219], off sc1
	s_waitcnt vmcnt(31)
; __device__ __forceinline__ unsigned pk2(float lo, float hi) { return pg8::cvt_pk_bf16(lo, hi); }
; __device__ __forceinline__ f32x4 ld4bf(const bf16* p) { const v2u w = *(const v2u*)p; return (f32x4){bf_lo(w.x), bf_hi(w.x), bf_lo(w.y), bf_hi(w.y)}; }
; __device__ __forceinline__ void pool_prep(const bf16* X, const float* ss, const float* gain, bf16* PB, LAS unsigned char* lds, int vcu, int G, int tid) {
;     ...
;         for (int i = 0; i < 32; ++i) { const int row = ra + i, t = row - bstart;
;             const f32x4 xn = ld4bf(xp + (size_t)row * DM) * rsl[row - r0 + 16];
;             f32x4 old = {0.f, 0.f, 0.f, 0.f};
;             if (t >= w) old = ld4bf(xp + (size_t)(row - w) * DM) * rsl[row - w - r0 + 16];
;             S = S + xn - old;
;             const int cnt = (t + 1 < w) ? t + 1 : w;
;             const f32x4 p = (S * (1.0f / (float)cnt) - xn) * gn;
;             v2u o; o.x = pk2(p[0], p[1]); o.y = pk2(p[2], p[3]); *(v2u*)(PB + (size_t)row * DM + 4 * q) = o; }
	v_lshlrev_b32_e32 v200, 16, v122
	v_and_b32_e32 v201, 0xffff0000, v122
	v_lshlrev_b32_e32 v202, 16, v123
	v_and_b32_e32 v203, 0xffff0000, v123
	v_mul_f32_e32 v204, v51, v200
	v_mul_f32_e32 v205, v51, v201
	v_mul_f32_e32 v206, v51, v202
	v_mul_f32_e32 v207, v51, v203
	v_fma_f32 v6, v51, v200, v6
	v_fma_f32 v7, v51, v201, v7
	v_fma_f32 v8, v51, v202, v8
	v_fma_f32 v9, v51, v203, v9
	v_lshlrev_b32_e32 v88, 16, v118
	v_and_b32_e32 v89, 0xffff0000, v118
	v_lshlrev_b32_e32 v90, 16, v119
	v_and_b32_e32 v91, 0xffff0000, v119
	v_mul_f32_e32 v88, v49, v88
	v_mul_f32_e32 v89, v49, v89
	v_mul_f32_e32 v90, v49, v90
	v_mul_f32_e32 v91, v49, v91
	v_sub_f32_e32 v6, v6, v88
	v_sub_f32_e32 v7, v7, v89
	v_sub_f32_e32 v8, v8, v90
	v_sub_f32_e32 v9, v9, v91
	v_fma_f32 v214, v197, v6, -v204
	v_fma_f32 v215, v197, v7, -v205
	v_fma_f32 v216, v197, v8, -v206
	v_fma_f32 v217, v197, v9, -v207
	v_mul_f32_e32 v214, v2, v214
	v_mul_f32_e32 v215, v3, v215
	v_mul_f32_e32 v216, v4, v216
	v_mul_f32_e32 v217, v5, v217
	v_cvt_pk_bf16_f32 v218, v214, v215
	v_cvt_pk_bf16_f32 v219, v216, v217
	global_store_dwordx2 v[24:25], v[218:219], off offset:2048 sc1
	s_mov_b64 s[0:1], 0x1000
	v_lshl_add_u64 v[24:25], v[24:25], 0, s[0:1]
	s_waitcnt vmcnt(31)
	v_lshlrev_b32_e32 v200, 16, v124
	v_and_b32_e32 v201, 0xffff0000, v124
	v_lshlrev_b32_e32 v202, 16, v125
	v_and_b32_e32 v203, 0xffff0000, v125
	v_mul_f32_e32 v204, v52, v200
	v_mul_f32_e32 v205, v52, v201
	v_mul_f32_e32 v206, v52, v202
	v_mul_f32_e32 v207, v52, v203
	v_fma_f32 v6, v52, v200, v6
	v_fma_f32 v7, v52, v201, v7
	v_fma_f32 v8, v52, v202, v8
	v_fma_f32 v9, v52, v203, v9
	v_lshlrev_b32_e32 v88, 16, v120
	v_and_b32_e32 v89, 0xffff0000, v120
	v_lshlrev_b32_e32 v90, 16, v121
	v_and_b32_e32 v91, 0xffff0000, v121
	v_mul_f32_e32 v88, v50, v88
	v_mul_f32_e32 v89, v50, v89
	v_mul_f32_e32 v90, v50, v90
	v_mul_f32_e32 v91, v50, v91
	v_sub_f32_e32 v6, v6, v88
	v_sub_f32_e32 v7, v7, v89
	v_sub_f32_e32 v8, v8, v90
	v_sub_f32_e32 v9, v9, v91
	v_fma_f32 v214, v197, v6, -v204
	v_fma_f32 v215, v197, v7, -v205
	v_fma_f32 v216, v197, v8, -v206
	v_fma_f32 v217, v197, v9, -v207
	v_mul_f32_e32 v214, v2, v214
	v_mul_f32_e32 v215, v3, v215
	v_mul_f32_e32 v216, v4, v216
	v_mul_f32_e32 v217, v5, v217
	v_cvt_pk_bf16_f32 v218, v214, v215
	v_cvt_pk_bf16_f32 v219, v216, v217
	global_store_dwordx2 v[24:25], v[218:219], off sc1
	s_waitcnt vmcnt(31)
	v_lshlrev_b32_e32 v200, 16, v126
	v_and_b32_e32 v201, 0xffff0000, v126
	v_lshlrev_b32_e32 v202, 16, v127
	v_and_b32_e32 v203, 0xffff0000, v127
	v_mul_f32_e32 v204, v53, v200
	v_mul_f32_e32 v205, v53, v201
	v_mul_f32_e32 v206, v53, v202
	v_mul_f32_e32 v207, v53, v203
	v_fma_f32 v6, v53, v200, v6
	v_fma_f32 v7, v53, v201, v7
	v_fma_f32 v8, v53, v202, v8
	v_fma_f32 v9, v53, v203, v9
	v_lshlrev_b32_e32 v88, 16, v122
	v_and_b32_e32 v89, 0xffff0000, v122
	v_lshlrev_b32_e32 v90, 16, v123
	v_and_b32_e32 v91, 0xffff0000, v123
	v_mul_f32_e32 v88, v51, v88
	v_mul_f32_e32 v89, v51, v89
	v_mul_f32_e32 v90, v51, v90
	v_mul_f32_e32 v91, v51, v91
	v_sub_f32_e32 v6, v6, v88
	v_sub_f32_e32 v7, v7, v89
	v_sub_f32_e32 v8, v8, v90
	v_sub_f32_e32 v9, v9, v91
	v_fma_f32 v214, v197, v6, -v204
	v_fma_f32 v215, v197, v7, -v205
	v_fma_f32 v216, v197, v8, -v206
	v_fma_f32 v217, v197, v9, -v207
	v_mul_f32_e32 v214, v2, v214
	v_mul_f32_e32 v215, v3, v215
	v_mul_f32_e32 v216, v4, v216
	v_mul_f32_e32 v217, v5, v217
	v_cvt_pk_bf16_f32 v218, v214, v215
	v_cvt_pk_bf16_f32 v219, v216, v217
	global_store_dwordx2 v[24:25], v[218:219], off offset:2048 sc1
	s_mov_b64 s[0:1], 0x1000
	v_lshl_add_u64 v[24:25], v[24:25], 0, s[0:1]
	s_waitcnt vmcnt(31)
	v_lshlrev_b32_e32 v200, 16, v128
	v_and_b32_e32 v201, 0xffff0000, v128
	v_lshlrev_b32_e32 v202, 16, v129
	v_and_b32_e32 v203, 0xffff0000, v129
	v_mul_f32_e32 v204, v54, v200
	v_mul_f32_e32 v205, v54, v201
	v_mul_f32_e32 v206, v54, v202
	v_mul_f32_e32 v207, v54, v203
	v_fma_f32 v6, v54, v200, v6
	v_fma_f32 v7, v54, v201, v7
	v_fma_f32 v8, v54, v202, v8
	v_fma_f32 v9, v54, v203, v9
	v_lshlrev_b32_e32 v88, 16, v124
	v_and_b32_e32 v89, 0xffff0000, v124
	v_lshlrev_b32_e32 v90, 16, v125
	v_and_b32_e32 v91, 0xffff0000, v125
	v_mul_f32_e32 v88, v52, v88
	v_mul_f32_e32 v89, v52, v89
	v_mul_f32_e32 v90, v52, v90
	v_mul_f32_e32 v91, v52, v91
	v_sub_f32_e32 v6, v6, v88
	v_sub_f32_e32 v7, v7, v89
	v_sub_f32_e32 v8, v8, v90
	v_sub_f32_e32 v9, v9, v91
	v_fma_f32 v214, v197, v6, -v204
	v_fma_f32 v215, v197, v7, -v205
	v_fma_f32 v216, v197, v8, -v206
	v_fma_f32 v217, v197, v9, -v207
	v_mul_f32_e32 v214, v2, v214
	v_mul_f32_e32 v215, v3, v215
	v_mul_f32_e32 v216, v4, v216
	v_mul_f32_e32 v217, v5, v217
	v_cvt_pk_bf16_f32 v218, v214, v215
	v_cvt_pk_bf16_f32 v219, v216, v217
	global_store_dwordx2 v[24:25], v[218:219], off sc1
	s_waitcnt vmcnt(31)
	v_lshlrev_b32_e32 v200, 16, v130
	v_and_b32_e32 v201, 0xffff0000, v130
	v_lshlrev_b32_e32 v202, 16, v131
	v_and_b32_e32 v203, 0xffff0000, v131
	v_mul_f32_e32 v204, v55, v200
	v_mul_f32_e32 v205, v55, v201
	v_mul_f32_e32 v206, v55, v202
	v_mul_f32_e32 v207, v55, v203
	v_fma_f32 v6, v55, v200, v6
	v_fma_f32 v7, v55, v201, v7
	v_fma_f32 v8, v55, v202, v8
	v_fma_f32 v9, v55, v203, v9
	v_lshlrev_b32_e32 v88, 16, v126
	v_and_b32_e32 v89, 0xffff0000, v126
	v_lshlrev_b32_e32 v90, 16, v127
	v_and_b32_e32 v91, 0xffff0000, v127
	v_mul_f32_e32 v88, v53, v88
	v_mul_f32_e32 v89, v53, v89
	v_mul_f32_e32 v90, v53, v90
	v_mul_f32_e32 v91, v53, v91
	v_sub_f32_e32 v6, v6, v88
	v_sub_f32_e32 v7, v7, v89
	v_sub_f32_e32 v8, v8, v90
	v_sub_f32_e32 v9, v9, v91
	v_fma_f32 v214, v197, v6, -v204
	v_fma_f32 v215, v197, v7, -v205
	v_fma_f32 v216, v197, v8, -v206
	v_fma_f32 v217, v197, v9, -v207
	v_mul_f32_e32 v214, v2, v214
	v_mul_f32_e32 v215, v3, v215
	v_mul_f32_e32 v216, v4, v216
	v_mul_f32_e32 v217, v5, v217
	v_cvt_pk_bf16_f32 v218, v214, v215
	v_cvt_pk_bf16_f32 v219, v216, v217
	global_store_dwordx2 v[24:25], v[218:219], off offset:2048 sc1
	s_mov_b64 s[0:1], 0x1000
	v_lshl_add_u64 v[24:25], v[24:25], 0, s[0:1]
	s_waitcnt vmcnt(31)
; __device__ __forceinline__ unsigned pk2(float lo, float hi) { return pg8::cvt_pk_bf16(lo, hi); }
; __device__ __forceinline__ f32x4 ld4bf(const bf16* p) { const v2u w = *(const v2u*)p; return (f32x4){bf_lo(w.x), bf_hi(w.x), bf_lo(w.y), bf_hi(w.y)}; }
; __device__ __forceinline__ void pool_prep(const bf16* X, const float* ss, const float* gain, bf16* PB, LAS unsigned char* lds, int vcu, int G, int tid) {
;     ...
;         for (int i = 0; i < 32; ++i) { const int row = ra + i, t = row - bstart;
;             const f32x4 xn = ld4bf(xp + (size_t)row * DM) * rsl[row - r0 + 16];
;             f32x4 old = {0.f, 0.f, 0.f, 0.f};
;             if (t >= w) old = ld4bf(xp + (size_t)(row - w) * DM) * rsl[row - w - r0 + 16];
;             S = S + xn - old;
;             const int cnt = (t + 1 < w) ? t + 1 : w;
;             const f32x4 p = (S * (1.0f / (float)cnt) - xn) * gn;
;             v2u o; o.x = pk2(p[0], p[1]); o.y = pk2(p[2], p[3]); *(v2u*)(PB + (size_t)row * DM + 4 * q) = o; }
	v_lshlrev_b32_e32 v200, 16, v132
	v_and_b32_e32 v201, 0xffff0000, v132
	v_lshlrev_b32_e32 v202, 16, v133
	v_and_b32_e32 v203, 0xffff0000, v133
	v_mul_f32_e32 v204, v56, v200
	v_mul_f32_e32 v205, v56, v201
	v_mul_f32_e32 v206, v56, v202
	v_mul_f32_e32 v207, v56, v203
	v_fma_f32 v6, v56, v200, v6
	v_fma_f32 v7, v56, v201, v7
	v_fma_f32 v8, v56, v202, v8
	v_fma_f32 v9, v56, v203, v9
	v_lshlrev_b32_e32 v88, 16, v128
	v_and_b32_e32 v89, 0xffff0000, v128
	v_lshlrev_b32_e32 v90, 16, v129
	v_and_b32_e32 v91, 0xffff0000, v129
	v_mul_f32_e32 v88, v54, v88
	v_mul_f32_e32 v89, v54, v89
	v_mul_f32_e32 v90, v54, v90
	v_mul_f32_e32 v91, v54, v91
	v_sub_f32_e32 v6, v6, v88
	v_sub_f32_e32 v7, v7, v89
	v_sub_f32_e32 v8, v8, v90
	v_sub_f32_e32 v9, v9, v91
	v_fma_f32 v214, v197, v6, -v204
	v_fma_f32 v215, v197, v7, -v205
	v_fma_f32 v216, v197, v8, -v206
	v_fma_f32 v217, v197, v9, -v207
	v_mul_f32_e32 v214, v2, v214
	v_mul_f32_e32 v215, v3, v215
	v_mul_f32_e32 v216, v4, v216
	v_mul_f32_e32 v217, v5, v217
	v_cvt_pk_bf16_f32 v218, v214, v215
	v_cvt_pk_bf16_f32 v219, v216, v217
	global_store_dwordx2 v[24:25], v[218:219], off sc1
	s_waitcnt vmcnt(31)
	v_lshlrev_b32_e32 v200, 16, v134
	v_and_b32_e32 v201, 0xffff0000, v134
	v_lshlrev_b32_e32 v202, 16, v135
	v_and_b32_e32 v203, 0xffff0000, v135
	v_mul_f32_e32 v204, v57, v200
	v_mul_f32_e32 v205, v57, v201
	v_mul_f32_e32 v206, v57, v202
	v_mul_f32_e32 v207, v57, v203
	v_fma_f32 v6, v57, v200, v6
	v_fma_f32 v7, v57, v201, v7
	v_fma_f32 v8, v57, v202, v8
	v_fma_f32 v9, v57, v203, v9
	v_lshlrev_b32_e32 v88, 16, v130
	v_and_b32_e32 v89, 0xffff0000, v130
	v_lshlrev_b32_e32 v90, 16, v131
	v_and_b32_e32 v91, 0xffff0000, v131
	v_mul_f32_e32 v88, v55, v88
	v_mul_f32_e32 v89, v55, v89
	v_mul_f32_e32 v90, v55, v90
	v_mul_f32_e32 v91, v55, v91
	v_sub_f32_e32 v6, v6, v88
	v_sub_f32_e32 v7, v7, v89
	v_sub_f32_e32 v8, v8, v90
	v_sub_f32_e32 v9, v9, v91
	v_fma_f32 v214, v197, v6, -v204
	v_fma_f32 v215, v197, v7, -v205
	v_fma_f32 v216, v197, v8, -v206
	v_fma_f32 v217, v197, v9, -v207
	v_mul_f32_e32 v214, v2, v214
	v_mul_f32_e32 v215, v3, v215
	v_mul_f32_e32 v216, v4, v216
	v_mul_f32_e32 v217, v5, v217
	v_cvt_pk_bf16_f32 v218, v214, v215
	v_cvt_pk_bf16_f32 v219, v216, v217
	global_store_dwordx2 v[24:25], v[218:219], off offset:2048 sc1
	s_mov_b64 s[0:1], 0x1000
	v_lshl_add_u64 v[24:25], v[24:25], 0, s[0:1]
	s_waitcnt vmcnt(31)
	v_lshlrev_b32_e32 v200, 16, v136
	v_and_b32_e32 v201, 0xffff0000, v136
	v_lshlrev_b32_e32 v202, 16, v137
	v_and_b32_e32 v203, 0xffff0000, v137
	v_mul_f32_e32 v204, v58, v200
	v_mul_f32_e32 v205, v58, v201
	v_mul_f32_e32 v206, v58, v202
	v_mul_f32_e32 v207, v58, v203
	v_fma_f32 v6, v58, v200, v6
	v_fma_f32 v7, v58, v201, v7
	v_fma_f32 v8, v58, v202, v8
	v_fma_f32 v9, v58, v203, v9
	v_lshlrev_b32_e32 v88, 16, v132
	v_and_b32_e32 v89, 0xffff0000, v132
	v_lshlrev_b32_e32 v90, 16, v133
	v_and_b32_e32 v91, 0xffff0000, v133
	v_mul_f32_e32 v88, v56, v88
	v_mul_f32_e32 v89, v56, v89
	v_mul_f32_e32 v90, v56, v90
	v_mul_f32_e32 v91, v56, v91
	v_sub_f32_e32 v6, v6, v88
	v_sub_f32_e32 v7, v7, v89
	v_sub_f32_e32 v8, v8, v90
	v_sub_f32_e32 v9, v9, v91
	v_fma_f32 v214, v197, v6, -v204
	v_fma_f32 v215, v197, v7, -v205
	v_fma_f32 v216, v197, v8, -v206
	v_fma_f32 v217, v197, v9, -v207
	v_mul_f32_e32 v214, v2, v214
	v_mul_f32_e32 v215, v3, v215
	v_mul_f32_e32 v216, v4, v216
	v_mul_f32_e32 v217, v5, v217
	v_cvt_pk_bf16_f32 v218, v214, v215
	v_cvt_pk_bf16_f32 v219, v216, v217
	global_store_dwordx2 v[24:25], v[218:219], off sc1
	s_waitcnt vmcnt(31)
	v_lshlrev_b32_e32 v200, 16, v138
	v_and_b32_e32 v201, 0xffff0000, v138
	v_lshlrev_b32_e32 v202, 16, v139
	v_and_b32_e32 v203, 0xffff0000, v139
	v_mul_f32_e32 v204, v59, v200
	v_mul_f32_e32 v205, v59, v201
	v_mul_f32_e32 v206, v59, v202
	v_mul_f32_e32 v207, v59, v203
	v_fma_f32 v6, v59, v200, v6
	v_fma_f32 v7, v59, v201, v7
	v_fma_f32 v8, v59, v202, v8
	v_fma_f32 v9, v59, v203, v9
	v_lshlrev_b32_e32 v88, 16, v134
	v_and_b32_e32 v89, 0xffff0000, v134
	v_lshlrev_b32_e32 v90, 16, v135
	v_and_b32_e32 v91, 0xffff0000, v135
	v_mul_f32_e32 v88, v57, v88
	v_mul_f32_e32 v89, v57, v89
	v_mul_f32_e32 v90, v57, v90
	v_mul_f32_e32 v91, v57, v91
	v_sub_f32_e32 v6, v6, v88
	v_sub_f32_e32 v7, v7, v89
	v_sub_f32_e32 v8, v8, v90
	v_sub_f32_e32 v9, v9, v91
	v_fma_f32 v214, v197, v6, -v204
	v_fma_f32 v215, v197, v7, -v205
	v_fma_f32 v216, v197, v8, -v206
	v_fma_f32 v217, v197, v9, -v207
	v_mul_f32_e32 v214, v2, v214
	v_mul_f32_e32 v215, v3, v215
	v_mul_f32_e32 v216, v4, v216
	v_mul_f32_e32 v217, v5, v217
	v_cvt_pk_bf16_f32 v218, v214, v215
	v_cvt_pk_bf16_f32 v219, v216, v217
	global_store_dwordx2 v[24:25], v[218:219], off offset:2048 sc1
	s_mov_b64 s[0:1], 0x1000
	v_lshl_add_u64 v[24:25], v[24:25], 0, s[0:1]
	s_waitcnt vmcnt(31)
	v_lshlrev_b32_e32 v200, 16, v140
	v_and_b32_e32 v201, 0xffff0000, v140
	v_lshlrev_b32_e32 v202, 16, v141
	v_and_b32_e32 v203, 0xffff0000, v141
	v_mul_f32_e32 v204, v60, v200
	v_mul_f32_e32 v205, v60, v201
	v_mul_f32_e32 v206, v60, v202
	v_mul_f32_e32 v207, v60, v203
	v_fma_f32 v6, v60, v200, v6
	v_fma_f32 v7, v60, v201, v7
	v_fma_f32 v8, v60, v202, v8
	v_fma_f32 v9, v60, v203, v9
	v_lshlrev_b32_e32 v88, 16, v136
	v_and_b32_e32 v89, 0xffff0000, v136
	v_lshlrev_b32_e32 v90, 16, v137
	v_and_b32_e32 v91, 0xffff0000, v137
	v_mul_f32_e32 v88, v58, v88
	v_mul_f32_e32 v89, v58, v89
	v_mul_f32_e32 v90, v58, v90
	v_mul_f32_e32 v91, v58, v91
	v_sub_f32_e32 v6, v6, v88
	v_sub_f32_e32 v7, v7, v89
	v_sub_f32_e32 v8, v8, v90
	v_sub_f32_e32 v9, v9, v91
	v_fma_f32 v214, v197, v6, -v204
	v_fma_f32 v215, v197, v7, -v205
	v_fma_f32 v216, v197, v8, -v206
	v_fma_f32 v217, v197, v9, -v207
	v_mul_f32_e32 v214, v2, v214
	v_mul_f32_e32 v215, v3, v215
	v_mul_f32_e32 v216, v4, v216
	v_mul_f32_e32 v217, v5, v217
	v_cvt_pk_bf16_f32 v218, v214, v215
	v_cvt_pk_bf16_f32 v219, v216, v217
	global_store_dwordx2 v[24:25], v[218:219], off sc1
	s_waitcnt vmcnt(31)
; __device__ __forceinline__ unsigned pk2(float lo, float hi) { return pg8::cvt_pk_bf16(lo, hi); }
; __device__ __forceinline__ f32x4 ld4bf(const bf16* p) { const v2u w = *(const v2u*)p; return (f32x4){bf_lo(w.x), bf_hi(w.x), bf_lo(w.y), bf_hi(w.y)}; }
; __device__ __forceinline__ void pool_prep(const bf16* X, const float* ss, const float* gain, bf16* PB, LAS unsigned char* lds, int vcu, int G, int tid) {
;     ...
;         for (int i = 0; i < 32; ++i) { const int row = ra + i, t = row - bstart;
;             const f32x4 xn = ld4bf(xp + (size_t)row * DM) * rsl[row - r0 + 16];
;             f32x4 old = {0.f, 0.f, 0.f, 0.f};
;             if (t >= w) old = ld4bf(xp + (size_t)(row - w) * DM) * rsl[row - w - r0 + 16];
;             S = S + xn - old;
;             const int cnt = (t + 1 < w) ? t + 1 : w;
;             const f32x4 p = (S * (1.0f / (float)cnt) - xn) * gn;
;             v2u o; o.x = pk2(p[0], p[1]); o.y = pk2(p[2], p[3]); *(v2u*)(PB + (size_t)row * DM + 4 * q) = o; }
	v_lshlrev_b32_e32 v200, 16, v142
	v_and_b32_e32 v201, 0xffff0000, v142
	v_lshlrev_b32_e32 v202, 16, v143
	v_and_b32_e32 v203, 0xffff0000, v143
	v_mul_f32_e32 v204, v61, v200
	v_mul_f32_e32 v205, v61, v201
	v_mul_f32_e32 v206, v61, v202
	v_mul_f32_e32 v207, v61, v203
	v_fma_f32 v6, v61, v200, v6
	v_fma_f32 v7, v61, v201, v7
	v_fma_f32 v8, v61, v202, v8
	v_fma_f32 v9, v61, v203, v9
	v_lshlrev_b32_e32 v88, 16, v138
	v_and_b32_e32 v89, 0xffff0000, v138
	v_lshlrev_b32_e32 v90, 16, v139
	v_and_b32_e32 v91, 0xffff0000, v139
	v_mul_f32_e32 v88, v59, v88
	v_mul_f32_e32 v89, v59, v89
	v_mul_f32_e32 v90, v59, v90
	v_mul_f32_e32 v91, v59, v91
	v_sub_f32_e32 v6, v6, v88
	v_sub_f32_e32 v7, v7, v89
	v_sub_f32_e32 v8, v8, v90
	v_sub_f32_e32 v9, v9, v91
	v_fma_f32 v214, v197, v6, -v204
	v_fma_f32 v215, v197, v7, -v205
	v_fma_f32 v216, v197, v8, -v206
	v_fma_f32 v217, v197, v9, -v207
	v_mul_f32_e32 v214, v2, v214
	v_mul_f32_e32 v215, v3, v215
	v_mul_f32_e32 v216, v4, v216
	v_mul_f32_e32 v217, v5, v217
	v_cvt_pk_bf16_f32 v218, v214, v215
	v_cvt_pk_bf16_f32 v219, v216, v217
	global_store_dwordx2 v[24:25], v[218:219], off offset:2048 sc1
	s_mov_b64 s[0:1], 0x1000
	v_lshl_add_u64 v[24:25], v[24:25], 0, s[0:1]
	s_waitcnt vmcnt(31)
	v_lshlrev_b32_e32 v200, 16, v144
	v_and_b32_e32 v201, 0xffff0000, v144
	v_lshlrev_b32_e32 v202, 16, v145
	v_and_b32_e32 v203, 0xffff0000, v145
	v_mul_f32_e32 v204, v62, v200
	v_mul_f32_e32 v205, v62, v201
	v_mul_f32_e32 v206, v62, v202
	v_mul_f32_e32 v207, v62, v203
	v_fma_f32 v6, v62, v200, v6
	v_fma_f32 v7, v62, v201, v7
	v_fma_f32 v8, v62, v202, v8
	v_fma_f32 v9, v62, v203, v9
	v_lshlrev_b32_e32 v88, 16, v140
	v_and_b32_e32 v89, 0xffff0000, v140
	v_lshlrev_b32_e32 v90, 16, v141
	v_and_b32_e32 v91, 0xffff0000, v141
	v_mul_f32_e32 v88, v60, v88
	v_mul_f32_e32 v89, v60, v89
	v_mul_f32_e32 v90, v60, v90
	v_mul_f32_e32 v91, v60, v91
	v_sub_f32_e32 v6, v6, v88
	v_sub_f32_e32 v7, v7, v89
	v_sub_f32_e32 v8, v8, v90
	v_sub_f32_e32 v9, v9, v91
	v_fma_f32 v214, v197, v6, -v204
	v_fma_f32 v215, v197, v7, -v205
	v_fma_f32 v216, v197, v8, -v206
	v_fma_f32 v217, v197, v9, -v207
	v_mul_f32_e32 v214, v2, v214
	v_mul_f32_e32 v215, v3, v215
	v_mul_f32_e32 v216, v4, v216
	v_mul_f32_e32 v217, v5, v217
	v_cvt_pk_bf16_f32 v218, v214, v215
	v_cvt_pk_bf16_f32 v219, v216, v217
	global_store_dwordx2 v[24:25], v[218:219], off sc1
	s_waitcnt vmcnt(31)
	v_lshlrev_b32_e32 v200, 16, v146
	v_and_b32_e32 v201, 0xffff0000, v146
	v_lshlrev_b32_e32 v202, 16, v147
	v_and_b32_e32 v203, 0xffff0000, v147
	v_mul_f32_e32 v204, v63, v200
	v_mul_f32_e32 v205, v63, v201
	v_mul_f32_e32 v206, v63, v202
	v_mul_f32_e32 v207, v63, v203
	v_fma_f32 v6, v63, v200, v6
	v_fma_f32 v7, v63, v201, v7
	v_fma_f32 v8, v63, v202, v8
	v_fma_f32 v9, v63, v203, v9
	v_lshlrev_b32_e32 v88, 16, v142
	v_and_b32_e32 v89, 0xffff0000, v142
	v_lshlrev_b32_e32 v90, 16, v143
	v_and_b32_e32 v91, 0xffff0000, v143
	v_mul_f32_e32 v88, v61, v88
	v_mul_f32_e32 v89, v61, v89
	v_mul_f32_e32 v90, v61, v90
	v_mul_f32_e32 v91, v61, v91
	v_sub_f32_e32 v6, v6, v88
	v_sub_f32_e32 v7, v7, v89
	v_sub_f32_e32 v8, v8, v90
	v_sub_f32_e32 v9, v9, v91
	v_fma_f32 v214, v197, v6, -v204
	v_fma_f32 v215, v197, v7, -v205
	v_fma_f32 v216, v197, v8, -v206
	v_fma_f32 v217, v197, v9, -v207
	v_mul_f32_e32 v214, v2, v214
	v_mul_f32_e32 v215, v3, v215
	v_mul_f32_e32 v216, v4, v216
	v_mul_f32_e32 v217, v5, v217
	v_cvt_pk_bf16_f32 v218, v214, v215
	v_cvt_pk_bf16_f32 v219, v216, v217
	global_store_dwordx2 v[24:25], v[218:219], off offset:2048 sc1
	s_mov_b64 s[0:1], 0x1000
	v_lshl_add_u64 v[24:25], v[24:25], 0, s[0:1]
	s_waitcnt vmcnt(31)
	v_lshlrev_b32_e32 v200, 16, v148
	v_and_b32_e32 v201, 0xffff0000, v148
	v_lshlrev_b32_e32 v202, 16, v149
	v_and_b32_e32 v203, 0xffff0000, v149
	v_mul_f32_e32 v204, v64, v200
	v_mul_f32_e32 v205, v64, v201
	v_mul_f32_e32 v206, v64, v202
	v_mul_f32_e32 v207, v64, v203
	v_fma_f32 v6, v64, v200, v6
	v_fma_f32 v7, v64, v201, v7
	v_fma_f32 v8, v64, v202, v8
	v_fma_f32 v9, v64, v203, v9
	v_lshlrev_b32_e32 v88, 16, v144
	v_and_b32_e32 v89, 0xffff0000, v144
	v_lshlrev_b32_e32 v90, 16, v145
	v_and_b32_e32 v91, 0xffff0000, v145
	v_mul_f32_e32 v88, v62, v88
	v_mul_f32_e32 v89, v62, v89
	v_mul_f32_e32 v90, v62, v90
	v_mul_f32_e32 v91, v62, v91
	v_sub_f32_e32 v6, v6, v88
	v_sub_f32_e32 v7, v7, v89
	v_sub_f32_e32 v8, v8, v90
	v_sub_f32_e32 v9, v9, v91
	v_fma_f32 v214, v197, v6, -v204
	v_fma_f32 v215, v197, v7, -v205
	v_fma_f32 v216, v197, v8, -v206
	v_fma_f32 v217, v197, v9, -v207
	v_mul_f32_e32 v214, v2, v214
	v_mul_f32_e32 v215, v3, v215
	v_mul_f32_e32 v216, v4, v216
	v_mul_f32_e32 v217, v5, v217
	v_cvt_pk_bf16_f32 v218, v214, v215
	v_cvt_pk_bf16_f32 v219, v216, v217
	global_store_dwordx2 v[24:25], v[218:219], off sc1
	s_waitcnt vmcnt(31)
	v_lshlrev_b32_e32 v200, 16, v150
	v_and_b32_e32 v201, 0xffff0000, v150
	v_lshlrev_b32_e32 v202, 16, v151
	v_and_b32_e32 v203, 0xffff0000, v151
	v_mul_f32_e32 v204, v65, v200
	v_mul_f32_e32 v205, v65, v201
	v_mul_f32_e32 v206, v65, v202
	v_mul_f32_e32 v207, v65, v203
	v_fma_f32 v6, v65, v200, v6
	v_fma_f32 v7, v65, v201, v7
	v_fma_f32 v8, v65, v202, v8
	v_fma_f32 v9, v65, v203, v9
	v_lshlrev_b32_e32 v88, 16, v146
	v_and_b32_e32 v89, 0xffff0000, v146
	v_lshlrev_b32_e32 v90, 16, v147
	v_and_b32_e32 v91, 0xffff0000, v147
	v_mul_f32_e32 v88, v63, v88
	v_mul_f32_e32 v89, v63, v89
	v_mul_f32_e32 v90, v63, v90
	v_mul_f32_e32 v91, v63, v91
	v_sub_f32_e32 v6, v6, v88
	v_sub_f32_e32 v7, v7, v89
	v_sub_f32_e32 v8, v8, v90
	v_sub_f32_e32 v9, v9, v91
	v_fma_f32 v214, v197, v6, -v204
	v_fma_f32 v215, v197, v7, -v205
	v_fma_f32 v216, v197, v8, -v206
	v_fma_f32 v217, v197, v9, -v207
	v_mul_f32_e32 v214, v2, v214
	v_mul_f32_e32 v215, v3, v215
	v_mul_f32_e32 v216, v4, v216
	v_mul_f32_e32 v217, v5, v217
	v_cvt_pk_bf16_f32 v218, v214, v215
	v_cvt_pk_bf16_f32 v219, v216, v217
	global_store_dwordx2 v[24:25], v[218:219], off offset:2048 sc1
	s_mov_b64 s[0:1], 0x1000
	v_lshl_add_u64 v[24:25], v[24:25], 0, s[0:1]
	s_waitcnt vmcnt(31)
; __device__ __forceinline__ unsigned pk2(float lo, float hi) { return pg8::cvt_pk_bf16(lo, hi); }
; __device__ __forceinline__ f32x4 ld4bf(const bf16* p) { const v2u w = *(const v2u*)p; return (f32x4){bf_lo(w.x), bf_hi(w.x), bf_lo(w.y), bf_hi(w.y)}; }
; __device__ __forceinline__ void pool_prep(const bf16* X, const float* ss, const float* gain, bf16* PB, LAS unsigned char* lds, int vcu, int G, int tid) {
;     ...
;         for (int i = 0; i < 32; ++i) { const int row = ra + i, t = row - bstart;
;             const f32x4 xn = ld4bf(xp + (size_t)row * DM) * rsl[row - r0 + 16];
;             f32x4 old = {0.f, 0.f, 0.f, 0.f};
;             if (t >= w) old = ld4bf(xp + (size_t)(row - w) * DM) * rsl[row - w - r0 + 16];
;             S = S + xn - old;
;             const int cnt = (t + 1 < w) ? t + 1 : w;
;             const f32x4 p = (S * (1.0f / (float)cnt) - xn) * gn;
;             v2u o; o.x = pk2(p[0], p[1]); o.y = pk2(p[2], p[3]); *(v2u*)(PB + (size_t)row * DM + 4 * q) = o; }
	v_lshlrev_b32_e32 v200, 16, v152
	v_and_b32_e32 v201, 0xffff0000, v152
	v_lshlrev_b32_e32 v202, 16, v153
	v_and_b32_e32 v203, 0xffff0000, v153
	v_mul_f32_e32 v204, v66, v200
	v_mul_f32_e32 v205, v66, v201
	v_mul_f32_e32 v206, v66, v202
	v_mul_f32_e32 v207, v66, v203
	v_fma_f32 v6, v66, v200, v6
	v_fma_f32 v7, v66, v201, v7
	v_fma_f32 v8, v66, v202, v8
	v_fma_f32 v9, v66, v203, v9
	v_lshlrev_b32_e32 v88, 16, v148
	v_and_b32_e32 v89, 0xffff0000, v148
	v_lshlrev_b32_e32 v90, 16, v149
	v_and_b32_e32 v91, 0xffff0000, v149
	v_mul_f32_e32 v88, v64, v88
	v_mul_f32_e32 v89, v64, v89
	v_mul_f32_e32 v90, v64, v90
	v_mul_f32_e32 v91, v64, v91
	v_sub_f32_e32 v6, v6, v88
	v_sub_f32_e32 v7, v7, v89
	v_sub_f32_e32 v8, v8, v90
	v_sub_f32_e32 v9, v9, v91
	v_fma_f32 v214, v197, v6, -v204
	v_fma_f32 v215, v197, v7, -v205
	v_fma_f32 v216, v197, v8, -v206
	v_fma_f32 v217, v197, v9, -v207
	v_mul_f32_e32 v214, v2, v214
	v_mul_f32_e32 v215, v3, v215
	v_mul_f32_e32 v216, v4, v216
	v_mul_f32_e32 v217, v5, v217
	v_cvt_pk_bf16_f32 v218, v214, v215
	v_cvt_pk_bf16_f32 v219, v216, v217
	global_store_dwordx2 v[24:25], v[218:219], off sc1
	s_waitcnt vmcnt(31)
	v_lshlrev_b32_e32 v200, 16, v154
	v_and_b32_e32 v201, 0xffff0000, v154
	v_lshlrev_b32_e32 v202, 16, v155
	v_and_b32_e32 v203, 0xffff0000, v155
	v_mul_f32_e32 v204, v67, v200
	v_mul_f32_e32 v205, v67, v201
	v_mul_f32_e32 v206, v67, v202
	v_mul_f32_e32 v207, v67, v203
	v_fma_f32 v6, v67, v200, v6
	v_fma_f32 v7, v67, v201, v7
	v_fma_f32 v8, v67, v202, v8
	v_fma_f32 v9, v67, v203, v9
	v_lshlrev_b32_e32 v88, 16, v150
	v_and_b32_e32 v89, 0xffff0000, v150
	v_lshlrev_b32_e32 v90, 16, v151
	v_and_b32_e32 v91, 0xffff0000, v151
	v_mul_f32_e32 v88, v65, v88
	v_mul_f32_e32 v89, v65, v89
	v_mul_f32_e32 v90, v65, v90
	v_mul_f32_e32 v91, v65, v91
	v_sub_f32_e32 v6, v6, v88
	v_sub_f32_e32 v7, v7, v89
	v_sub_f32_e32 v8, v8, v90
	v_sub_f32_e32 v9, v9, v91
	v_fma_f32 v214, v197, v6, -v204
	v_fma_f32 v215, v197, v7, -v205
	v_fma_f32 v216, v197, v8, -v206
	v_fma_f32 v217, v197, v9, -v207
	v_mul_f32_e32 v214, v2, v214
	v_mul_f32_e32 v215, v3, v215
	v_mul_f32_e32 v216, v4, v216
	v_mul_f32_e32 v217, v5, v217
	v_cvt_pk_bf16_f32 v218, v214, v215
	v_cvt_pk_bf16_f32 v219, v216, v217
	global_store_dwordx2 v[24:25], v[218:219], off offset:2048 sc1
	s_mov_b64 s[0:1], 0x1000
	v_lshl_add_u64 v[24:25], v[24:25], 0, s[0:1]
	s_waitcnt vmcnt(31)
	v_lshlrev_b32_e32 v200, 16, v156
	v_and_b32_e32 v201, 0xffff0000, v156
	v_lshlrev_b32_e32 v202, 16, v157
	v_and_b32_e32 v203, 0xffff0000, v157
	v_mul_f32_e32 v204, v68, v200
	v_mul_f32_e32 v205, v68, v201
	v_mul_f32_e32 v206, v68, v202
	v_mul_f32_e32 v207, v68, v203
	v_fma_f32 v6, v68, v200, v6
	v_fma_f32 v7, v68, v201, v7
	v_fma_f32 v8, v68, v202, v8
	v_fma_f32 v9, v68, v203, v9
	v_lshlrev_b32_e32 v88, 16, v152
	v_and_b32_e32 v89, 0xffff0000, v152
	v_lshlrev_b32_e32 v90, 16, v153
	v_and_b32_e32 v91, 0xffff0000, v153
	v_mul_f32_e32 v88, v66, v88
	v_mul_f32_e32 v89, v66, v89
	v_mul_f32_e32 v90, v66, v90
	v_mul_f32_e32 v91, v66, v91
	v_sub_f32_e32 v6, v6, v88
	v_sub_f32_e32 v7, v7, v89
	v_sub_f32_e32 v8, v8, v90
	v_sub_f32_e32 v9, v9, v91
	v_fma_f32 v214, v197, v6, -v204
	v_fma_f32 v215, v197, v7, -v205
	v_fma_f32 v216, v197, v8, -v206
	v_fma_f32 v217, v197, v9, -v207
	v_mul_f32_e32 v214, v2, v214
	v_mul_f32_e32 v215, v3, v215
	v_mul_f32_e32 v216, v4, v216
	v_mul_f32_e32 v217, v5, v217
	v_cvt_pk_bf16_f32 v218, v214, v215
	v_cvt_pk_bf16_f32 v219, v216, v217
	global_store_dwordx2 v[24:25], v[218:219], off sc1
	s_waitcnt vmcnt(31)
	v_lshlrev_b32_e32 v200, 16, v158
	v_and_b32_e32 v201, 0xffff0000, v158
	v_lshlrev_b32_e32 v202, 16, v159
	v_and_b32_e32 v203, 0xffff0000, v159
	v_mul_f32_e32 v204, v69, v200
	v_mul_f32_e32 v205, v69, v201
	v_mul_f32_e32 v206, v69, v202
	v_mul_f32_e32 v207, v69, v203
	v_fma_f32 v6, v69, v200, v6
	v_fma_f32 v7, v69, v201, v7
	v_fma_f32 v8, v69, v202, v8
	v_fma_f32 v9, v69, v203, v9
	v_lshlrev_b32_e32 v88, 16, v154
	v_and_b32_e32 v89, 0xffff0000, v154
	v_lshlrev_b32_e32 v90, 16, v155
	v_and_b32_e32 v91, 0xffff0000, v155
	v_mul_f32_e32 v88, v67, v88
	v_mul_f32_e32 v89, v67, v89
	v_mul_f32_e32 v90, v67, v90
	v_mul_f32_e32 v91, v67, v91
	v_sub_f32_e32 v6, v6, v88
	v_sub_f32_e32 v7, v7, v89
	v_sub_f32_e32 v8, v8, v90
	v_sub_f32_e32 v9, v9, v91
	v_fma_f32 v214, v197, v6, -v204
	v_fma_f32 v215, v197, v7, -v205
	v_fma_f32 v216, v197, v8, -v206
	v_fma_f32 v217, v197, v9, -v207
	v_mul_f32_e32 v214, v2, v214
	v_mul_f32_e32 v215, v3, v215
	v_mul_f32_e32 v216, v4, v216
	v_mul_f32_e32 v217, v5, v217
	v_cvt_pk_bf16_f32 v218, v214, v215
	v_cvt_pk_bf16_f32 v219, v216, v217
	global_store_dwordx2 v[24:25], v[218:219], off offset:2048 sc1
	s_mov_b64 s[0:1], 0x1000
	v_lshl_add_u64 v[24:25], v[24:25], 0, s[0:1]
	s_waitcnt vmcnt(31)
; __device__ __forceinline__ unsigned pk2(float lo, float hi) { return pg8::cvt_pk_bf16(lo, hi); }
; __device__ __forceinline__ f32x4 ld4bf(const bf16* p) { const v2u w = *(const v2u*)p; return (f32x4){bf_lo(w.x), bf_hi(w.x), bf_lo(w.y), bf_hi(w.y)}; }
; __device__ __forceinline__ void pool_prep(const bf16* X, const float* ss, const float* gain, bf16* PB, LAS unsigned char* lds, int vcu, int G, int tid) {
;     ...
;         for (int i = 0; i < 32; ++i) { const int row = ra + i, t = row - bstart;
;             const f32x4 xn = ld4bf(xp + (size_t)row * DM) * rsl[row - r0 + 16];
;             f32x4 old = {0.f, 0.f, 0.f, 0.f};
;             if (t >= w) old = ld4bf(xp + (size_t)(row - w) * DM) * rsl[row - w - r0 + 16];
;             S = S + xn - old;
;             const int cnt = (t + 1 < w) ? t + 1 : w;
;             const f32x4 p = (S * (1.0f / (float)cnt) - xn) * gn;
;             v2u o; o.x = pk2(p[0], p[1]); o.y = pk2(p[2], p[3]); *(v2u*)(PB + (size_t)row * DM + 4 * q) = o; }
	v_lshlrev_b32_e32 v200, 16, v160
	v_and_b32_e32 v201, 0xffff0000, v160
	v_lshlrev_b32_e32 v202, 16, v161
	v_and_b32_e32 v203, 0xffff0000, v161
	v_mul_f32_e32 v204, v70, v200
	v_mul_f32_e32 v205, v70, v201
	v_mul_f32_e32 v206, v70, v202
	v_mul_f32_e32 v207, v70, v203
	v_fma_f32 v6, v70, v200, v6
	v_fma_f32 v7, v70, v201, v7
	v_fma_f32 v8, v70, v202, v8
	v_fma_f32 v9, v70, v203, v9
	v_lshlrev_b32_e32 v88, 16, v156
	v_and_b32_e32 v89, 0xffff0000, v156
	v_lshlrev_b32_e32 v90, 16, v157
	v_and_b32_e32 v91, 0xffff0000, v157
	v_mul_f32_e32 v88, v68, v88
	v_mul_f32_e32 v89, v68, v89
	v_mul_f32_e32 v90, v68, v90
	v_mul_f32_e32 v91, v68, v91
	v_sub_f32_e32 v6, v6, v88
	v_sub_f32_e32 v7, v7, v89
	v_sub_f32_e32 v8, v8, v90
	v_sub_f32_e32 v9, v9, v91
	v_fma_f32 v214, v197, v6, -v204
	v_fma_f32 v215, v197, v7, -v205
	v_fma_f32 v216, v197, v8, -v206
	v_fma_f32 v217, v197, v9, -v207
	v_mul_f32_e32 v214, v2, v214
	v_mul_f32_e32 v215, v3, v215
	v_mul_f32_e32 v216, v4, v216
	v_mul_f32_e32 v217, v5, v217
	v_cvt_pk_bf16_f32 v218, v214, v215
	v_cvt_pk_bf16_f32 v219, v216, v217
	global_store_dwordx2 v[24:25], v[218:219], off sc1
	s_waitcnt vmcnt(31)
	v_lshlrev_b32_e32 v200, 16, v162
	v_and_b32_e32 v201, 0xffff0000, v162
	v_lshlrev_b32_e32 v202, 16, v163
	v_and_b32_e32 v203, 0xffff0000, v163
	v_mul_f32_e32 v204, v71, v200
	v_mul_f32_e32 v205, v71, v201
	v_mul_f32_e32 v206, v71, v202
	v_mul_f32_e32 v207, v71, v203
	v_fma_f32 v6, v71, v200, v6
	v_fma_f32 v7, v71, v201, v7
	v_fma_f32 v8, v71, v202, v8
	v_fma_f32 v9, v71, v203, v9
	v_lshlrev_b32_e32 v88, 16, v158
	v_and_b32_e32 v89, 0xffff0000, v158
	v_lshlrev_b32_e32 v90, 16, v159
	v_and_b32_e32 v91, 0xffff0000, v159
	v_mul_f32_e32 v88, v69, v88
	v_mul_f32_e32 v89, v69, v89
	v_mul_f32_e32 v90, v69, v90
	v_mul_f32_e32 v91, v69, v91
	v_sub_f32_e32 v6, v6, v88
	v_sub_f32_e32 v7, v7, v89
	v_sub_f32_e32 v8, v8, v90
	v_sub_f32_e32 v9, v9, v91
	v_fma_f32 v214, v197, v6, -v204
	v_fma_f32 v215, v197, v7, -v205
	v_fma_f32 v216, v197, v8, -v206
	v_fma_f32 v217, v197, v9, -v207
	v_mul_f32_e32 v214, v2, v214
	v_mul_f32_e32 v215, v3, v215
	v_mul_f32_e32 v216, v4, v216
	v_mul_f32_e32 v217, v5, v217
	v_cvt_pk_bf16_f32 v218, v214, v215
	v_cvt_pk_bf16_f32 v219, v216, v217
	global_store_dwordx2 v[24:25], v[218:219], off offset:2048 sc1
	s_mov_b64 s[0:1], 0x1000
	v_lshl_add_u64 v[24:25], v[24:25], 0, s[0:1]
	s_waitcnt vmcnt(31)
	v_lshlrev_b32_e32 v200, 16, v164
	v_and_b32_e32 v201, 0xffff0000, v164
	v_lshlrev_b32_e32 v202, 16, v165
	v_and_b32_e32 v203, 0xffff0000, v165
	v_mul_f32_e32 v204, v72, v200
	v_mul_f32_e32 v205, v72, v201
	v_mul_f32_e32 v206, v72, v202
	v_mul_f32_e32 v207, v72, v203
	v_fma_f32 v6, v72, v200, v6
	v_fma_f32 v7, v72, v201, v7
	v_fma_f32 v8, v72, v202, v8
	v_fma_f32 v9, v72, v203, v9
	v_lshlrev_b32_e32 v88, 16, v160
	v_and_b32_e32 v89, 0xffff0000, v160
	v_lshlrev_b32_e32 v90, 16, v161
	v_and_b32_e32 v91, 0xffff0000, v161
	v_mul_f32_e32 v88, v70, v88
	v_mul_f32_e32 v89, v70, v89
	v_mul_f32_e32 v90, v70, v90
	v_mul_f32_e32 v91, v70, v91
	v_sub_f32_e32 v6, v6, v88
	v_sub_f32_e32 v7, v7, v89
	v_sub_f32_e32 v8, v8, v90
	v_sub_f32_e32 v9, v9, v91
	v_fma_f32 v214, v197, v6, -v204
	v_fma_f32 v215, v197, v7, -v205
	v_fma_f32 v216, v197, v8, -v206
	v_fma_f32 v217, v197, v9, -v207
	v_mul_f32_e32 v214, v2, v214
	v_mul_f32_e32 v215, v3, v215
	v_mul_f32_e32 v216, v4, v216
	v_mul_f32_e32 v217, v5, v217
	v_cvt_pk_bf16_f32 v218, v214, v215
	v_cvt_pk_bf16_f32 v219, v216, v217
	global_store_dwordx2 v[24:25], v[218:219], off sc1
	s_waitcnt vmcnt(31)
	v_lshlrev_b32_e32 v200, 16, v166
	v_and_b32_e32 v201, 0xffff0000, v166
	v_lshlrev_b32_e32 v202, 16, v167
	v_and_b32_e32 v203, 0xffff0000, v167
	v_mul_f32_e32 v204, v73, v200
	v_mul_f32_e32 v205, v73, v201
	v_mul_f32_e32 v206, v73, v202
	v_mul_f32_e32 v207, v73, v203
	v_fma_f32 v6, v73, v200, v6
	v_fma_f32 v7, v73, v201, v7
	v_fma_f32 v8, v73, v202, v8
	v_fma_f32 v9, v73, v203, v9
	v_lshlrev_b32_e32 v88, 16, v162
	v_and_b32_e32 v89, 0xffff0000, v162
	v_lshlrev_b32_e32 v90, 16, v163
	v_and_b32_e32 v91, 0xffff0000, v163
	v_mul_f32_e32 v88, v71, v88
	v_mul_f32_e32 v89, v71, v89
	v_mul_f32_e32 v90, v71, v90
	v_mul_f32_e32 v91, v71, v91
	v_sub_f32_e32 v6, v6, v88
	v_sub_f32_e32 v7, v7, v89
	v_sub_f32_e32 v8, v8, v90
	v_sub_f32_e32 v9, v9, v91
	v_fma_f32 v214, v197, v6, -v204
	v_fma_f32 v215, v197, v7, -v205
	v_fma_f32 v216, v197, v8, -v206
	v_fma_f32 v217, v197, v9, -v207
	v_mul_f32_e32 v214, v2, v214
	v_mul_f32_e32 v215, v3, v215
	v_mul_f32_e32 v216, v4, v216
	v_mul_f32_e32 v217, v5, v217
	v_cvt_pk_bf16_f32 v218, v214, v215
	v_cvt_pk_bf16_f32 v219, v216, v217
	global_store_dwordx2 v[24:25], v[218:219], off offset:2048 sc1
	s_branch .LBB0_308
.Lmy_hop636:
	s_branch .LBB0_636
.Lmy_hop635:
	s_branch .LBB0_635
.Lmy_hop2:
	s_branch .LBB0_2
.Lmy_hop3:
	s_branch .LBB0_3
.LBB0_363:
	s_mov_b64 s[0:1], 0
